# attention queue: during a unit's last K/V tile every wave touches the next item's Q rows, gate rows and first K/V tile (L2 warm-up); next index broadcast through LDS
# speedup vs baseline: 1.0101x; 1.0000x over previous
.LBB0_262:
	v_mov_b32_e32 v0, v212
	s_nop 1
	v_permlane32_swap_b32_e32 v212, v0
	v_add_f32_e32 v0, v212, v0
	v_div_scale_f32 v2, s[0:1], v0, v0, 1.0
	v_rcp_f32_e32 v4, v2
	v_add3_u32 v8, s61, v177, v176
	v_lshlrev_b32_e32 v9, 4, v145
	s_waitcnt vmcnt(3)
	v_fma_f32 v3, -v2, v4, 1.0
	v_fmac_f32_e32 v4, v3, v4
	v_div_scale_f32 v3, vcc, 1.0, v0, 1.0
	v_mul_f32_e32 v5, v3, v4
	v_fma_f32 v6, -v2, v5, v3
	v_fmac_f32_e32 v5, v6, v4
	v_add_u32_e32 v10, v8, v9
	v_fma_f32 v6, -v2, v5, v3
	ds_read_b64 v[2:3], v10
	v_div_fmas_f32 v4, v6, v4, v5
	v_div_fixup_f32 v0, v4, v0, 1.0
	v_pk_mul_f32 v[4:5], v[64:65], v[0:1] op_sel_hi:[1,0]
	s_mulk_i32 s90, 0x1400
	s_waitcnt lgkmcnt(0)
	v_lshlrev_b32_e32 v6, 16, v2
	v_and_b32_e32 v7, 0xffff0000, v2
	v_pk_mul_f32 v[4:5], v[4:5], v[6:7]
	v_lshlrev_b32_e32 v6, 16, v3
	v_cvt_pk_bf16_f32 v2, v4, v5
	v_pk_mul_f32 v[4:5], v[66:67], v[0:1] op_sel_hi:[1,0]
	v_and_b32_e32 v7, 0xffff0000, v3
	v_pk_mul_f32 v[4:5], v[4:5], v[6:7]
	s_mul_hi_u32 s0, s89, 0x1400
	v_cvt_pk_bf16_f32 v3, v4, v5
	ds_write_b64 v10, v[2:3]
	v_xad_u32 v10, v9, 16, v8
	ds_read_b64 v[2:3], v10
	v_pk_mul_f32 v[4:5], v[68:69], v[0:1] op_sel_hi:[1,0]
	s_add_i32 s0, s0, s90
	s_mulk_i32 s89, 0x1400
	s_add_u32 s1, s30, s89
	s_waitcnt lgkmcnt(0)
	v_lshlrev_b32_e32 v6, 16, v2
	v_and_b32_e32 v7, 0xffff0000, v2
	v_pk_mul_f32 v[4:5], v[4:5], v[6:7]
	v_lshlrev_b32_e32 v6, 16, v3
	v_cvt_pk_bf16_f32 v2, v4, v5
	v_pk_mul_f32 v[4:5], v[70:71], v[0:1] op_sel_hi:[1,0]
	v_and_b32_e32 v7, 0xffff0000, v3
	v_pk_mul_f32 v[4:5], v[4:5], v[6:7]
	s_addc_u32 s2, s31, s0
	v_cvt_pk_bf16_f32 v3, v4, v5
	ds_write_b64 v10, v[2:3]
	v_xad_u32 v10, v9, 32, v8
	ds_read_b64 v[2:3], v10
	v_pk_mul_f32 v[4:5], v[72:73], v[0:1] op_sel_hi:[1,0]
	s_add_u32 s0, s1, s60
	s_addc_u32 s1, s2, 0
	v_mov_b32_e32 v145, v1
	s_waitcnt lgkmcnt(0)
	v_lshlrev_b32_e32 v6, 16, v2
	v_and_b32_e32 v7, 0xffff0000, v2
	v_pk_mul_f32 v[4:5], v[4:5], v[6:7]
	v_lshlrev_b32_e32 v6, 16, v3
	v_cvt_pk_bf16_f32 v2, v4, v5
	v_pk_mul_f32 v[4:5], v[74:75], v[0:1] op_sel_hi:[1,0]
	v_and_b32_e32 v7, 0xffff0000, v3
	v_pk_mul_f32 v[4:5], v[4:5], v[6:7]
	s_mov_b64 s[2:3], s[22:23]
	v_cvt_pk_bf16_f32 v3, v4, v5
	ds_write_b64 v10, v[2:3]
	v_xad_u32 v10, v9, 48, v8
	ds_read_b64 v[2:3], v10
	v_pk_mul_f32 v[4:5], v[76:77], v[0:1] op_sel_hi:[1,0]
	s_waitcnt lgkmcnt(0)
	v_lshlrev_b32_e32 v6, 16, v2
	v_and_b32_e32 v7, 0xffff0000, v2
	v_pk_mul_f32 v[4:5], v[4:5], v[6:7]
	v_lshlrev_b32_e32 v6, 16, v3
	v_cvt_pk_bf16_f32 v2, v4, v5
	v_pk_mul_f32 v[4:5], v[78:79], v[0:1] op_sel_hi:[1,0]
	v_and_b32_e32 v7, 0xffff0000, v3
	v_pk_mul_f32 v[4:5], v[4:5], v[6:7]
	s_nop 0
	v_cvt_pk_bf16_f32 v3, v4, v5
	ds_write_b64 v10, v[2:3]
	v_xad_u32 v10, v9, 64, v8
	ds_read_b64 v[2:3], v10
	v_pk_mul_f32 v[4:5], v[48:49], v[0:1] op_sel_hi:[1,0]
	s_waitcnt lgkmcnt(0)
	v_lshlrev_b32_e32 v6, 16, v2
	v_and_b32_e32 v7, 0xffff0000, v2
	v_pk_mul_f32 v[4:5], v[4:5], v[6:7]
	v_lshlrev_b32_e32 v6, 16, v3
	v_cvt_pk_bf16_f32 v2, v4, v5
	v_pk_mul_f32 v[4:5], v[50:51], v[0:1] op_sel_hi:[1,0]
	v_and_b32_e32 v7, 0xffff0000, v3
	v_pk_mul_f32 v[4:5], v[4:5], v[6:7]
	s_nop 0
	v_cvt_pk_bf16_f32 v3, v4, v5
	ds_write_b64 v10, v[2:3]
	v_xad_u32 v10, v9, s69, v8
	ds_read_b64 v[2:3], v10
	v_pk_mul_f32 v[4:5], v[52:53], v[0:1] op_sel_hi:[1,0]
	s_waitcnt lgkmcnt(0)
	v_lshlrev_b32_e32 v6, 16, v2
	v_and_b32_e32 v7, 0xffff0000, v2
	v_pk_mul_f32 v[4:5], v[4:5], v[6:7]
	v_lshlrev_b32_e32 v6, 16, v3
	v_cvt_pk_bf16_f32 v2, v4, v5
	v_pk_mul_f32 v[4:5], v[54:55], v[0:1] op_sel_hi:[1,0]
	v_and_b32_e32 v7, 0xffff0000, v3
	v_pk_mul_f32 v[4:5], v[4:5], v[6:7]
	s_nop 0
	v_cvt_pk_bf16_f32 v3, v4, v5
	ds_write_b64 v10, v[2:3]
	v_xad_u32 v10, v9, s70, v8
	ds_read_b64 v[2:3], v10
	v_pk_mul_f32 v[4:5], v[56:57], v[0:1] op_sel_hi:[1,0]
	s_waitcnt lgkmcnt(0)
	v_lshlrev_b32_e32 v6, 16, v2
	v_and_b32_e32 v7, 0xffff0000, v2
	v_pk_mul_f32 v[4:5], v[4:5], v[6:7]
	v_lshlrev_b32_e32 v6, 16, v3
	v_cvt_pk_bf16_f32 v2, v4, v5
	v_pk_mul_f32 v[4:5], v[58:59], v[0:1] op_sel_hi:[1,0]
	v_and_b32_e32 v7, 0xffff0000, v3
	v_pk_mul_f32 v[4:5], v[4:5], v[6:7]
	s_nop 0
	v_cvt_pk_bf16_f32 v3, v4, v5
	ds_write_b64 v10, v[2:3]
	v_xad_u32 v10, v9, s71, v8
	ds_read_b64 v[2:3], v10
	v_pk_mul_f32 v[4:5], v[60:61], v[0:1] op_sel_hi:[1,0]
	s_waitcnt lgkmcnt(0)
	v_lshlrev_b32_e32 v6, 16, v2
	v_and_b32_e32 v7, 0xffff0000, v2
	v_pk_mul_f32 v[4:5], v[4:5], v[6:7]
	v_lshlrev_b32_e32 v6, 16, v3
	v_cvt_pk_bf16_f32 v2, v4, v5
	v_pk_mul_f32 v[4:5], v[62:63], v[0:1] op_sel_hi:[1,0]
	v_and_b32_e32 v7, 0xffff0000, v3
	v_pk_mul_f32 v[4:5], v[4:5], v[6:7]
	s_nop 0
	v_cvt_pk_bf16_f32 v3, v4, v5
	ds_write_b64 v10, v[2:3]
	v_xad_u32 v10, v9, s72, v8
	ds_read_b64 v[2:3], v10
	v_pk_mul_f32 v[4:5], v[32:33], v[0:1] op_sel_hi:[1,0]
	s_waitcnt lgkmcnt(0)
	v_lshlrev_b32_e32 v6, 16, v2
	v_and_b32_e32 v7, 0xffff0000, v2
	v_pk_mul_f32 v[4:5], v[4:5], v[6:7]
	v_lshlrev_b32_e32 v6, 16, v3
	v_cvt_pk_bf16_f32 v2, v4, v5
	v_pk_mul_f32 v[4:5], v[34:35], v[0:1] op_sel_hi:[1,0]
	v_and_b32_e32 v7, 0xffff0000, v3
	v_pk_mul_f32 v[4:5], v[4:5], v[6:7]
	s_nop 0
	v_cvt_pk_bf16_f32 v3, v4, v5
	ds_write_b64 v10, v[2:3]
	v_xad_u32 v10, v9, s73, v8
	ds_read_b64 v[2:3], v10
	v_pk_mul_f32 v[4:5], v[36:37], v[0:1] op_sel_hi:[1,0]
	s_waitcnt lgkmcnt(0)
	v_lshlrev_b32_e32 v6, 16, v2
	v_and_b32_e32 v7, 0xffff0000, v2
	v_pk_mul_f32 v[4:5], v[4:5], v[6:7]
	v_lshlrev_b32_e32 v6, 16, v3
	v_cvt_pk_bf16_f32 v2, v4, v5
	v_pk_mul_f32 v[4:5], v[38:39], v[0:1] op_sel_hi:[1,0]
	v_and_b32_e32 v7, 0xffff0000, v3
	v_pk_mul_f32 v[4:5], v[4:5], v[6:7]
	s_nop 0
	v_cvt_pk_bf16_f32 v3, v4, v5
	ds_write_b64 v10, v[2:3]
	v_xad_u32 v10, v9, s79, v8
	ds_read_b64 v[2:3], v10
	v_pk_mul_f32 v[4:5], v[40:41], v[0:1] op_sel_hi:[1,0]
	s_waitcnt lgkmcnt(0)
	v_lshlrev_b32_e32 v6, 16, v2
	v_and_b32_e32 v7, 0xffff0000, v2
	v_pk_mul_f32 v[4:5], v[4:5], v[6:7]
	v_lshlrev_b32_e32 v6, 16, v3
	v_cvt_pk_bf16_f32 v2, v4, v5
	v_pk_mul_f32 v[4:5], v[42:43], v[0:1] op_sel_hi:[1,0]
	v_and_b32_e32 v7, 0xffff0000, v3
	v_pk_mul_f32 v[4:5], v[4:5], v[6:7]
	s_nop 0
	v_cvt_pk_bf16_f32 v3, v4, v5
	ds_write_b64 v10, v[2:3]
	v_xad_u32 v10, v9, s80, v8
	ds_read_b64 v[2:3], v10
	v_pk_mul_f32 v[4:5], v[44:45], v[0:1] op_sel_hi:[1,0]
	s_waitcnt lgkmcnt(0)
	v_lshlrev_b32_e32 v6, 16, v2
	v_and_b32_e32 v7, 0xffff0000, v2
	v_pk_mul_f32 v[4:5], v[4:5], v[6:7]
	v_lshlrev_b32_e32 v6, 16, v3
	v_cvt_pk_bf16_f32 v2, v4, v5
	v_pk_mul_f32 v[4:5], v[46:47], v[0:1] op_sel_hi:[1,0]
	v_and_b32_e32 v7, 0xffff0000, v3
	v_pk_mul_f32 v[4:5], v[4:5], v[6:7]
	s_nop 0
	v_cvt_pk_bf16_f32 v3, v4, v5
	ds_write_b64 v10, v[2:3]
	v_xad_u32 v10, v9, s81, v8
	ds_read_b64 v[2:3], v10
	v_pk_mul_f32 v[4:5], v[16:17], v[0:1] op_sel_hi:[1,0]
	s_waitcnt lgkmcnt(0)
	v_lshlrev_b32_e32 v6, 16, v2
	v_and_b32_e32 v7, 0xffff0000, v2
	v_pk_mul_f32 v[4:5], v[4:5], v[6:7]
	v_lshlrev_b32_e32 v6, 16, v3
	v_cvt_pk_bf16_f32 v2, v4, v5
	v_pk_mul_f32 v[4:5], v[18:19], v[0:1] op_sel_hi:[1,0]
	v_and_b32_e32 v7, 0xffff0000, v3
	v_pk_mul_f32 v[4:5], v[4:5], v[6:7]
	s_nop 0
	v_cvt_pk_bf16_f32 v3, v4, v5
	ds_write_b64 v10, v[2:3]
	v_xad_u32 v10, v9, s82, v8
	ds_read_b64 v[2:3], v10
	v_pk_mul_f32 v[4:5], v[20:21], v[0:1] op_sel_hi:[1,0]
	s_waitcnt lgkmcnt(0)
	v_lshlrev_b32_e32 v6, 16, v2
	v_and_b32_e32 v7, 0xffff0000, v2
	v_pk_mul_f32 v[4:5], v[4:5], v[6:7]
	v_lshlrev_b32_e32 v6, 16, v3
	v_cvt_pk_bf16_f32 v2, v4, v5
	v_pk_mul_f32 v[4:5], v[22:23], v[0:1] op_sel_hi:[1,0]
	v_and_b32_e32 v7, 0xffff0000, v3
	v_pk_mul_f32 v[4:5], v[4:5], v[6:7]
	s_nop 0
	v_cvt_pk_bf16_f32 v3, v4, v5
	ds_write_b64 v10, v[2:3]
	v_xad_u32 v10, v9, s83, v8
	ds_read_b64 v[2:3], v10
	v_pk_mul_f32 v[4:5], v[24:25], v[0:1] op_sel_hi:[1,0]
	v_xad_u32 v8, v9, s84, v8
	s_waitcnt lgkmcnt(0)
	v_lshlrev_b32_e32 v6, 16, v2
	v_and_b32_e32 v7, 0xffff0000, v2
	v_pk_mul_f32 v[4:5], v[4:5], v[6:7]
	v_lshlrev_b32_e32 v6, 16, v3
	v_cvt_pk_bf16_f32 v2, v4, v5
	v_pk_mul_f32 v[4:5], v[26:27], v[0:1] op_sel_hi:[1,0]
	v_and_b32_e32 v7, 0xffff0000, v3
	v_pk_mul_f32 v[4:5], v[4:5], v[6:7]
	s_nop 0
	v_cvt_pk_bf16_f32 v3, v4, v5
	ds_write_b64 v10, v[2:3]
	ds_read_b64 v[2:3], v8
	v_pk_mul_f32 v[4:5], v[28:29], v[0:1] op_sel_hi:[1,0]
	s_waitcnt lgkmcnt(0)
	v_lshlrev_b32_e32 v6, 16, v2
	v_and_b32_e32 v7, 0xffff0000, v2
	v_pk_mul_f32 v[4:5], v[4:5], v[6:7]
	v_lshlrev_b32_e32 v6, 16, v3
	v_cvt_pk_bf16_f32 v2, v4, v5
	v_pk_mul_f32 v[4:5], v[30:31], v[0:1] op_sel_hi:[1,0]
	v_and_b32_e32 v7, 0xffff0000, v3
	v_pk_mul_f32 v[4:5], v[4:5], v[6:7]
	v_lshlrev_b32_e32 v0, 4, v174
	v_cvt_pk_bf16_f32 v3, v4, v5
	v_and_b32_e32 v0, 0xf0, v0
	ds_write_b64 v8, v[2:3]
	v_add_u32_e32 v18, s61, v0
	s_waitcnt lgkmcnt(0)
	v_lshl_add_u32 v6, v170, 8, v18
	ds_read_b128 v[2:5], v6
	v_mul_u32_u24_e32 v0, 0x1400, v170
	v_lshl_add_u64 v[14:15], s[0:1], 0, v[0:1]
	v_lshl_add_u64 v[10:11], v[14:15], 0, v[144:145]
	v_lshl_add_u32 v0, v147, 8, v18
	v_mov_b32_e32 v147, v1
	s_waitcnt lgkmcnt(0)
	global_store_dwordx4 v[10:11], v[2:5], off
	v_lshl_add_u64 v[10:11], v[14:15], 0, v[146:147]
	ds_read_b128 v[6:9], v6 offset:4096
	ds_read_b128 v[2:5], v0
	v_add_co_u32_e32 v16, vcc, s86, v10
	v_lshl_add_u32 v0, v149, 8, v18
	s_nop 0
	v_addc_co_u32_e32 v17, vcc, 0, v11, vcc
	ds_read_b128 v[10:13], v0
	v_lshl_add_u64 v[14:15], v[14:15], 0, s[48:49]
	v_mov_b32_e32 v149, v1
	s_waitcnt lgkmcnt(0)
	global_store_dwordx4 v[16:17], v[2:5], off
	v_lshl_add_u32 v0, v153, 8, v18
	v_mov_b32_e32 v153, v1
	v_lshl_add_u64 v[2:3], v[14:15], 0, v[148:149]
	global_store_dwordx4 v[2:3], v[10:13], off
	ds_read_b128 v[2:5], v0
	v_lshl_add_u32 v0, v151, 8, v18
	v_lshl_add_u64 v[10:11], v[14:15], 0, v[152:153]
	v_add_co_u32_e32 v14, vcc, s86, v10
	v_mov_b32_e32 v151, v1
	s_nop 0
	v_addc_co_u32_e32 v15, vcc, 0, v11, vcc
	ds_read_b128 v[10:13], v0
	v_mad_u32_u24 v0, v170, s85, v196
	s_waitcnt lgkmcnt(0)
	global_store_dwordx4 v[14:15], v[2:5], off
	s_nop 1
	v_lshl_add_u64 v[2:3], s[0:1], 0, v[0:1]
	v_lshl_add_u64 v[2:3], v[2:3], 0, v[144:145]
	v_mad_u32_u24 v0, v170, s85, v197
	global_store_dwordx4 v[2:3], v[6:9], off
	v_lshl_add_u64 v[2:3], s[0:1], 0, v[0:1]
	v_lshl_add_u64 v[2:3], v[2:3], 0, v[150:151]
	v_lshl_add_u32 v0, v155, 8, v18
	global_store_dwordx4 v[2:3], v[10:13], off
	ds_read_b128 v[2:5], v0
	v_mad_u32_u24 v0, v170, s85, v198
	v_lshl_add_u64 v[6:7], s[0:1], 0, v[0:1]
	v_mov_b32_e32 v155, v1
	v_lshl_add_u32 v0, v157, 8, v18
	v_lshl_add_u64 v[10:11], v[6:7], 0, v[154:155]
	ds_read_b128 v[6:9], v0
	v_mad_u32_u24 v0, v170, s85, v199
	s_waitcnt lgkmcnt(0)
	global_store_dwordx4 v[10:11], v[2:5], off
	v_mov_b32_e32 v157, v1
	s_nop 0
	v_lshl_add_u64 v[2:3], s[0:1], 0, v[0:1]
	v_lshl_add_u64 v[2:3], v[2:3], 0, v[156:157]
	global_store_dwordx4 v[2:3], v[6:9], off
	s_waitcnt lgkmcnt(0)

.LBB0_292:
	s_waitcnt vmcnt(0)
	s_mov_b64 s[100:101], exec
	s_mov_b64 exec, s[4:5]
	ds_write_b32 v173, v171 offset:4
	s_mov_b64 exec, s[100:101]
	s_waitcnt lgkmcnt(0)
	s_add_i32 s60, s52, 1
	s_cmp_ge_u32 s60, s56
	s_barrier
	s_cbranch_scc1 .Lpf_in_0
	s_cmp_lt_u32 s52, 3
	s_cselect_b32 s2, s20, 0xffffff00
	s_add_i32 s2, s2, s59
	s_add_i32 s2, s2, 64
	s_ashr_i32 s3, s2, 31
	s_add_i32 s53, s58, 0x4000
	s_and_b32 s53, s53, 0x4000
	v_lshl_add_u64 v[2:3], s[2:3], 0, v[158:159]
	v_mad_u64_u32 v[4:5], s[54:55], v2, s62, v[162:163]
	s_add_i32 s53, s53, 0
	v_mad_i32_i24 v5, v3, s62, v5
	s_add_i32 s61, s53, s95
	v_lshl_add_u64 v[4:5], v[4:5], 0, s[24:25]
	s_mov_b32 m0, s61
	s_add_i32 s53, s53, s96
	global_load_lds_dwordx4 v[4:5], off
	v_mad_u64_u32 v[4:5], s[54:55], v2, s62, v[164:165]
	v_mad_i32_i24 v5, v3, s62, v5
	s_add_i32 m0, s61, 0x8000
	v_lshl_add_u64 v[2:3], s[2:3], 0, v[160:161]
	global_load_lds_dwordx4 v[4:5], off
	v_mad_u64_u32 v[4:5], s[2:3], v2, s62, v[166:167]
	v_mad_i32_i24 v5, v3, s62, v5
	v_lshl_add_u64 v[4:5], v[4:5], 0, s[24:25]
	s_mov_b32 m0, s53
	s_nop 0
	global_load_lds_dwordx4 v[4:5], off
	v_mad_u64_u32 v[4:5], s[2:3], v2, s62, v[168:169]
	v_mad_i32_i24 v5, v3, s62, v5
	s_add_i32 m0, s53, 0x8000
	s_nop 0
	global_load_lds_dwordx4 v[4:5], off
	s_branch .LBB0_294
.Lpf_in_0:
	ds_read_b32 v246, v173 offset:4
	s_waitcnt lgkmcnt(0)
	v_readfirstlane_b32 s98, v246
	s_nop 3
	s_cmpk_ge_u32 s98, 0x700
	s_cbranch_scc1 .Lpf_done_0
	v_cmp_gt_u32_e32 vcc, 0x180, v246
	s_nop 1
	v_cndmask_b32_e64 v252, 0, 1, vcc
	v_cmp_gt_u32_e32 vcc, 0xc0, v246
	s_nop 1
	v_cndmask_b32_e64 v253, 0, 1, vcc
	v_mul_u32_u24_e32 v255, 0x5c0, v252
	v_mul_u32_u24_e32 v247, 0xc0, v253
	v_add_u32_e32 v255, v255, v247
	v_sub_u32_e32 v255, 0x680, v255
	v_sub_u32_e32 v255, v246, v255
	v_add_u32_e32 v252, v252, v253
	v_mad_u32_u24 v252, v252, 3, 1
	v_lshrrev_b32_e32 v253, 6, v255
	v_sub_u32_e32 v252, v252, v253
	v_bfe_u32 v247, v255, 3, 3
	v_lshlrev_b32_e32 v247, 11, v247
	v_lshl_add_u32 v247, v252, 8, v247
	v_and_b32_e32 v253, 7, v255
	v_lshlrev_b32_e32 v248, 8, v253
	v_mov_b32_e32 v249, 0x1800
	v_mov_b32_e32 v250, v247
	v_add_u32_e32 v251, 0x800, v248
	v_subrev_u32_e32 v255, 0x180, v246
	v_cmp_gt_u32_e32 vcc, 0x300, v255
	s_nop 3
	s_mov_b64 s[98:99], vcc
	v_bfe_u32 v246, v255, 5, 3
	v_lshlrev_b32_e32 v246, 11, v246
	v_and_b32_e32 v253, 7, v255
	v_lshl_add_u32 v252, v253, 8, v246
	v_cndmask_b32_e64 v247, v247, v252, s[98:99]
	v_lshlrev_b32_e32 v252, 8, v253
	v_and_b32_e32 v253, 0xfffffe00, v252
	v_cmp_le_u32_e32 vcc, 0x200, v255
	s_nop 1
	v_cndmask_b32_e32 v253, v253, v252, vcc
	v_cmp_le_u32_e32 vcc, 0x100, v255
	s_nop 1
	v_cndmask_b32_e64 v253, 0, v253, vcc
	v_subrev_u32_e32 v252, 0x80, v252
	v_max_i32_e32 v252, v252, v253
	v_add_u32_e32 v252, v252, v246
	v_cndmask_b32_e64 v250, v250, v252, s[98:99]
	v_lshrrev_b32_e32 v252, 8, v255
	v_bfe_u32 v253, v255, 3, 2
	v_lshl_add_u32 v252, v252, 2, v253
	v_lshlrev_b32_e32 v252, 8, v252
	v_add_u32_e32 v253, 0x2000, v252
	v_cndmask_b32_e64 v248, v248, v253, s[98:99]
	v_add_u32_e32 v253, 0x2c00, v252
	v_cndmask_b32_e64 v251, v251, v253, s[98:99]
	v_cndmask_b32_e64 v249, v249, 0, s[98:99]
	v_subrev_u32_e32 v255, 0x300, v255
	v_cmp_gt_u32_e32 vcc, 0x200, v255
	s_nop 3
	s_mov_b64 s[100:101], vcc
	v_lshrrev_b32_e32 v252, 6, v255
	v_lshlrev_b32_e32 v252, 11, v252
	v_bfe_u32 v253, v255, 1, 3
	v_lshl_add_u32 v252, v253, 8, v252
	v_cndmask_b32_e64 v247, v247, v252, s[100:101]
	v_cndmask_b32_e64 v250, v250, v252, s[100:101]
	v_bfe_u32 v252, v255, 4, 2
	v_lshlrev_b32_e32 v252, 9, v252
	v_add_u32_e32 v252, 0x4800, v252
	v_cndmask_b32_e64 v248, v248, v252, s[100:101]
	v_add_u32_e32 v253, 0x100, v252
	v_cndmask_b32_e64 v251, v251, v253, s[100:101]
	v_and_b32_e32 v252, 1, v255
	v_lshlrev_b32_e32 v252, 8, v252
	v_add_u32_e32 v252, 0x800, v252
	v_cndmask_b32_e64 v249, v249, v252, s[100:101]
	v_mov_b32_e32 v252, 0x800
	v_mov_b32_e32 v253, 0xc00
	v_cndmask_b32_e64 v252, v252, v253, s[98:99]
	v_mov_b32_e32 v253, 0x100
	v_cndmask_b32_e64 v252, v252, v253, s[100:101]
	v_lshrrev_b32_e32 v253, 1, v175
	v_add_u32_e32 v247, v247, v253
	v_mul_u32_u24_e32 v247, 0x5800, v247
	v_and_b32_e32 v253, 1, v175
	v_lshlrev_b32_e32 v253, 7, v253
	v_add3_u32 v246, v247, v248, v253
	v_add_u32_e32 v248, v246, v249
	v_lshrrev_b32_e32 v249, 3, v175
	v_add_u32_e32 v250, v250, v249
	v_mul_u32_u24_e32 v250, 0x5800, v250
	v_add3_u32 v250, v250, v251, v253
	v_bfe_u32 v249, v175, 1, 1
	v_mul_u32_u24_e32 v249, v249, v252
	v_add_u32_e32 v250, v250, v249
	v_mov_b32_e32 v247, 0
	v_mov_b32_e32 v249, 0
	v_mov_b32_e32 v251, 0
	s_add_u32 s100, s38, 0xba00000
	s_addc_u32 s101, s39, 0
	v_lshl_add_u64 v[246:247], s[100:101], 0, v[246:247]
	v_lshl_add_u64 v[248:249], s[100:101], 0, v[248:249]
	v_lshl_add_u64 v[250:251], s[100:101], 0, v[250:251]
	global_load_dword v255, v[246:247], off
	global_load_dword v255, v[248:249], off
	global_load_dword v255, v[250:251], off
.Lpf_done_0:
.LBB0_294:
	s_cmp_lt_u32 s52, 4
	s_cselect_b64 s[2:3], -1, 0
	s_cmp_gt_u32 s52, 3
	s_cbranch_scc0 .LBB0_296
	s_add_i32 s52, s52, -4
	s_lshr_b32 s52, s52, 2
	s_lshl_b32 s52, 1, s52
	s_lshr_b32 s52, s52, s94
	s_cmp_eq_u32 s52, 0
	v_cmp_eq_u32_e64 s[52:53], s52, 0
	s_cselect_b64 s[54:55], -1, 0
	s_cmp_eq_u64 s[52:53], 0
	s_cselect_b64 s[52:53], -1, 0
	v_cndmask_b32_e64 v80, v195, 0, s[54:55]
	s_cbranch_execz .LBB0_297
	s_branch .LBB0_298

.LBB0_304:
	v_mov_b32_e32 v0, v211
	s_nop 1
	v_permlane32_swap_b32_e32 v211, v0
	v_add_f32_e32 v0, v211, v0
	v_div_scale_f32 v2, s[2:3], v0, v0, 1.0
	v_rcp_f32_e32 v4, v2
	v_add3_u32 v8, s91, v177, v176
	v_lshlrev_b32_e32 v9, 4, v145
	s_waitcnt vmcnt(3)
	v_fma_f32 v3, -v2, v4, 1.0
	v_fmac_f32_e32 v4, v3, v4
	v_div_scale_f32 v3, vcc, 1.0, v0, 1.0
	v_mul_f32_e32 v5, v3, v4
	v_fma_f32 v6, -v2, v5, v3
	v_fmac_f32_e32 v5, v6, v4
	v_add_u32_e32 v10, v8, v9
	v_fma_f32 v6, -v2, v5, v3
	ds_read_b64 v[2:3], v10
	v_div_fmas_f32 v4, v6, v4, v5
	v_div_fixup_f32 v0, v4, v0, 1.0
	v_pk_mul_f32 v[4:5], v[64:65], v[0:1] op_sel_hi:[1,0]
	s_mulk_i32 s93, 0x1400
	s_waitcnt lgkmcnt(0)
	v_lshlrev_b32_e32 v6, 16, v2
	v_and_b32_e32 v7, 0xffff0000, v2
	v_pk_mul_f32 v[4:5], v[4:5], v[6:7]
	v_lshlrev_b32_e32 v6, 16, v3
	v_cvt_pk_bf16_f32 v2, v4, v5
	v_pk_mul_f32 v[4:5], v[66:67], v[0:1] op_sel_hi:[1,0]
	v_and_b32_e32 v7, 0xffff0000, v3
	v_pk_mul_f32 v[4:5], v[4:5], v[6:7]
	s_mul_hi_u32 s2, s92, 0x1400
	v_cvt_pk_bf16_f32 v3, v4, v5
	ds_write_b64 v10, v[2:3]
	v_xad_u32 v10, v9, 16, v8
	ds_read_b64 v[2:3], v10
	v_pk_mul_f32 v[4:5], v[68:69], v[0:1] op_sel_hi:[1,0]
	s_add_i32 s2, s2, s93
	s_mulk_i32 s92, 0x1400
	s_add_u32 s3, s30, s92
	s_waitcnt lgkmcnt(0)
	v_lshlrev_b32_e32 v6, 16, v2
	v_and_b32_e32 v7, 0xffff0000, v2
	v_pk_mul_f32 v[4:5], v[4:5], v[6:7]
	v_lshlrev_b32_e32 v6, 16, v3
	v_cvt_pk_bf16_f32 v2, v4, v5
	v_pk_mul_f32 v[4:5], v[70:71], v[0:1] op_sel_hi:[1,0]
	v_and_b32_e32 v7, 0xffff0000, v3
	v_pk_mul_f32 v[4:5], v[4:5], v[6:7]
	s_addc_u32 s20, s31, s2
	v_cvt_pk_bf16_f32 v3, v4, v5
	ds_write_b64 v10, v[2:3]
	v_xad_u32 v10, v9, 32, v8
	ds_read_b64 v[2:3], v10
	v_pk_mul_f32 v[4:5], v[72:73], v[0:1] op_sel_hi:[1,0]
	s_add_u32 s2, s3, s90
	s_addc_u32 s3, s20, 0
	v_mov_b32_e32 v145, v1
	s_waitcnt lgkmcnt(0)
	v_lshlrev_b32_e32 v6, 16, v2
	v_and_b32_e32 v7, 0xffff0000, v2
	v_pk_mul_f32 v[4:5], v[4:5], v[6:7]
	v_lshlrev_b32_e32 v6, 16, v3
	v_cvt_pk_bf16_f32 v2, v4, v5
	v_pk_mul_f32 v[4:5], v[74:75], v[0:1] op_sel_hi:[1,0]
	v_and_b32_e32 v7, 0xffff0000, v3
	v_pk_mul_f32 v[4:5], v[4:5], v[6:7]
	s_nop 0
	v_cvt_pk_bf16_f32 v3, v4, v5
	ds_write_b64 v10, v[2:3]
	v_xad_u32 v10, v9, 48, v8
	ds_read_b64 v[2:3], v10
	v_pk_mul_f32 v[4:5], v[76:77], v[0:1] op_sel_hi:[1,0]
	s_waitcnt lgkmcnt(0)
	v_lshlrev_b32_e32 v6, 16, v2
	v_and_b32_e32 v7, 0xffff0000, v2
	v_pk_mul_f32 v[4:5], v[4:5], v[6:7]
	v_lshlrev_b32_e32 v6, 16, v3
	v_cvt_pk_bf16_f32 v2, v4, v5
	v_pk_mul_f32 v[4:5], v[78:79], v[0:1] op_sel_hi:[1,0]
	v_and_b32_e32 v7, 0xffff0000, v3
	v_pk_mul_f32 v[4:5], v[4:5], v[6:7]
	s_nop 0
	v_cvt_pk_bf16_f32 v3, v4, v5
	ds_write_b64 v10, v[2:3]
	v_xad_u32 v10, v9, 64, v8
	ds_read_b64 v[2:3], v10
	v_pk_mul_f32 v[4:5], v[48:49], v[0:1] op_sel_hi:[1,0]
	s_waitcnt lgkmcnt(0)
	v_lshlrev_b32_e32 v6, 16, v2
	v_and_b32_e32 v7, 0xffff0000, v2
	v_pk_mul_f32 v[4:5], v[4:5], v[6:7]
	v_lshlrev_b32_e32 v6, 16, v3
	v_cvt_pk_bf16_f32 v2, v4, v5
	v_pk_mul_f32 v[4:5], v[50:51], v[0:1] op_sel_hi:[1,0]
	v_and_b32_e32 v7, 0xffff0000, v3
	v_pk_mul_f32 v[4:5], v[4:5], v[6:7]
	s_nop 0
	v_cvt_pk_bf16_f32 v3, v4, v5
	ds_write_b64 v10, v[2:3]
	v_xad_u32 v10, v9, s69, v8
	ds_read_b64 v[2:3], v10
	v_pk_mul_f32 v[4:5], v[52:53], v[0:1] op_sel_hi:[1,0]
	s_waitcnt lgkmcnt(0)
	v_lshlrev_b32_e32 v6, 16, v2
	v_and_b32_e32 v7, 0xffff0000, v2
	v_pk_mul_f32 v[4:5], v[4:5], v[6:7]
	v_lshlrev_b32_e32 v6, 16, v3
	v_cvt_pk_bf16_f32 v2, v4, v5
	v_pk_mul_f32 v[4:5], v[54:55], v[0:1] op_sel_hi:[1,0]
	v_and_b32_e32 v7, 0xffff0000, v3
	v_pk_mul_f32 v[4:5], v[4:5], v[6:7]
	s_nop 0
	v_cvt_pk_bf16_f32 v3, v4, v5
	ds_write_b64 v10, v[2:3]
	v_xad_u32 v10, v9, s70, v8
	ds_read_b64 v[2:3], v10
	v_pk_mul_f32 v[4:5], v[56:57], v[0:1] op_sel_hi:[1,0]
	s_waitcnt lgkmcnt(0)
	v_lshlrev_b32_e32 v6, 16, v2
	v_and_b32_e32 v7, 0xffff0000, v2
	v_pk_mul_f32 v[4:5], v[4:5], v[6:7]
	v_lshlrev_b32_e32 v6, 16, v3
	v_cvt_pk_bf16_f32 v2, v4, v5
	v_pk_mul_f32 v[4:5], v[58:59], v[0:1] op_sel_hi:[1,0]
	v_and_b32_e32 v7, 0xffff0000, v3
	v_pk_mul_f32 v[4:5], v[4:5], v[6:7]
	s_nop 0
	v_cvt_pk_bf16_f32 v3, v4, v5
	ds_write_b64 v10, v[2:3]
	v_xad_u32 v10, v9, s71, v8
	ds_read_b64 v[2:3], v10
	v_pk_mul_f32 v[4:5], v[60:61], v[0:1] op_sel_hi:[1,0]
	s_waitcnt lgkmcnt(0)
	v_lshlrev_b32_e32 v6, 16, v2
	v_and_b32_e32 v7, 0xffff0000, v2
	v_pk_mul_f32 v[4:5], v[4:5], v[6:7]
	v_lshlrev_b32_e32 v6, 16, v3
	v_cvt_pk_bf16_f32 v2, v4, v5
	v_pk_mul_f32 v[4:5], v[62:63], v[0:1] op_sel_hi:[1,0]
	v_and_b32_e32 v7, 0xffff0000, v3
	v_pk_mul_f32 v[4:5], v[4:5], v[6:7]
	s_nop 0
	v_cvt_pk_bf16_f32 v3, v4, v5
	ds_write_b64 v10, v[2:3]
	v_xad_u32 v10, v9, s72, v8
	ds_read_b64 v[2:3], v10
	v_pk_mul_f32 v[4:5], v[32:33], v[0:1] op_sel_hi:[1,0]
	s_waitcnt lgkmcnt(0)
	v_lshlrev_b32_e32 v6, 16, v2
	v_and_b32_e32 v7, 0xffff0000, v2
	v_pk_mul_f32 v[4:5], v[4:5], v[6:7]
	v_lshlrev_b32_e32 v6, 16, v3
	v_cvt_pk_bf16_f32 v2, v4, v5
	v_pk_mul_f32 v[4:5], v[34:35], v[0:1] op_sel_hi:[1,0]
	v_and_b32_e32 v7, 0xffff0000, v3
	v_pk_mul_f32 v[4:5], v[4:5], v[6:7]
	s_nop 0
	v_cvt_pk_bf16_f32 v3, v4, v5
	ds_write_b64 v10, v[2:3]
	v_xad_u32 v10, v9, s73, v8
	ds_read_b64 v[2:3], v10
	v_pk_mul_f32 v[4:5], v[36:37], v[0:1] op_sel_hi:[1,0]
	s_waitcnt lgkmcnt(0)
	v_lshlrev_b32_e32 v6, 16, v2
	v_and_b32_e32 v7, 0xffff0000, v2
	v_pk_mul_f32 v[4:5], v[4:5], v[6:7]
	v_lshlrev_b32_e32 v6, 16, v3
	v_cvt_pk_bf16_f32 v2, v4, v5
	v_pk_mul_f32 v[4:5], v[38:39], v[0:1] op_sel_hi:[1,0]
	v_and_b32_e32 v7, 0xffff0000, v3
	v_pk_mul_f32 v[4:5], v[4:5], v[6:7]
	s_nop 0
	v_cvt_pk_bf16_f32 v3, v4, v5
	ds_write_b64 v10, v[2:3]
	v_xad_u32 v10, v9, s79, v8
	ds_read_b64 v[2:3], v10
	v_pk_mul_f32 v[4:5], v[40:41], v[0:1] op_sel_hi:[1,0]
	s_waitcnt lgkmcnt(0)
	v_lshlrev_b32_e32 v6, 16, v2
	v_and_b32_e32 v7, 0xffff0000, v2
	v_pk_mul_f32 v[4:5], v[4:5], v[6:7]
	v_lshlrev_b32_e32 v6, 16, v3
	v_cvt_pk_bf16_f32 v2, v4, v5
	v_pk_mul_f32 v[4:5], v[42:43], v[0:1] op_sel_hi:[1,0]
	v_and_b32_e32 v7, 0xffff0000, v3
	v_pk_mul_f32 v[4:5], v[4:5], v[6:7]
	s_nop 0
	v_cvt_pk_bf16_f32 v3, v4, v5
	ds_write_b64 v10, v[2:3]
	v_xad_u32 v10, v9, s80, v8
	ds_read_b64 v[2:3], v10
	v_pk_mul_f32 v[4:5], v[44:45], v[0:1] op_sel_hi:[1,0]
	s_waitcnt lgkmcnt(0)
	v_lshlrev_b32_e32 v6, 16, v2
	v_and_b32_e32 v7, 0xffff0000, v2
	v_pk_mul_f32 v[4:5], v[4:5], v[6:7]
	v_lshlrev_b32_e32 v6, 16, v3
	v_cvt_pk_bf16_f32 v2, v4, v5
	v_pk_mul_f32 v[4:5], v[46:47], v[0:1] op_sel_hi:[1,0]
	v_and_b32_e32 v7, 0xffff0000, v3
	v_pk_mul_f32 v[4:5], v[4:5], v[6:7]
	s_nop 0
	v_cvt_pk_bf16_f32 v3, v4, v5
	ds_write_b64 v10, v[2:3]
	v_xad_u32 v10, v9, s81, v8
	ds_read_b64 v[2:3], v10
	v_pk_mul_f32 v[4:5], v[16:17], v[0:1] op_sel_hi:[1,0]
	s_waitcnt lgkmcnt(0)
	v_lshlrev_b32_e32 v6, 16, v2
	v_and_b32_e32 v7, 0xffff0000, v2
	v_pk_mul_f32 v[4:5], v[4:5], v[6:7]
	v_lshlrev_b32_e32 v6, 16, v3
	v_cvt_pk_bf16_f32 v2, v4, v5
	v_pk_mul_f32 v[4:5], v[18:19], v[0:1] op_sel_hi:[1,0]
	v_and_b32_e32 v7, 0xffff0000, v3
	v_pk_mul_f32 v[4:5], v[4:5], v[6:7]
	s_nop 0
	v_cvt_pk_bf16_f32 v3, v4, v5
	ds_write_b64 v10, v[2:3]
	v_xad_u32 v10, v9, s82, v8
	ds_read_b64 v[2:3], v10
	v_pk_mul_f32 v[4:5], v[20:21], v[0:1] op_sel_hi:[1,0]
	s_waitcnt lgkmcnt(0)
	v_lshlrev_b32_e32 v6, 16, v2
	v_and_b32_e32 v7, 0xffff0000, v2
	v_pk_mul_f32 v[4:5], v[4:5], v[6:7]
	v_lshlrev_b32_e32 v6, 16, v3
	v_cvt_pk_bf16_f32 v2, v4, v5
	v_pk_mul_f32 v[4:5], v[22:23], v[0:1] op_sel_hi:[1,0]
	v_and_b32_e32 v7, 0xffff0000, v3
	v_pk_mul_f32 v[4:5], v[4:5], v[6:7]
	s_nop 0
	v_cvt_pk_bf16_f32 v3, v4, v5
	ds_write_b64 v10, v[2:3]
	v_xad_u32 v10, v9, s83, v8
	ds_read_b64 v[2:3], v10
	v_pk_mul_f32 v[4:5], v[24:25], v[0:1] op_sel_hi:[1,0]
	v_xad_u32 v8, v9, s84, v8
	s_waitcnt lgkmcnt(0)
	v_lshlrev_b32_e32 v6, 16, v2
	v_and_b32_e32 v7, 0xffff0000, v2
	v_pk_mul_f32 v[4:5], v[4:5], v[6:7]
	v_lshlrev_b32_e32 v6, 16, v3
	v_cvt_pk_bf16_f32 v2, v4, v5
	v_pk_mul_f32 v[4:5], v[26:27], v[0:1] op_sel_hi:[1,0]
	v_and_b32_e32 v7, 0xffff0000, v3
	v_pk_mul_f32 v[4:5], v[4:5], v[6:7]
	s_nop 0
	v_cvt_pk_bf16_f32 v3, v4, v5
	ds_write_b64 v10, v[2:3]
	ds_read_b64 v[2:3], v8
	v_pk_mul_f32 v[4:5], v[28:29], v[0:1] op_sel_hi:[1,0]
	s_waitcnt lgkmcnt(0)
	v_lshlrev_b32_e32 v6, 16, v2
	v_and_b32_e32 v7, 0xffff0000, v2
	v_pk_mul_f32 v[4:5], v[4:5], v[6:7]
	v_lshlrev_b32_e32 v6, 16, v3
	v_cvt_pk_bf16_f32 v2, v4, v5
	v_pk_mul_f32 v[4:5], v[30:31], v[0:1] op_sel_hi:[1,0]
	v_and_b32_e32 v7, 0xffff0000, v3
	v_pk_mul_f32 v[4:5], v[4:5], v[6:7]
	v_lshlrev_b32_e32 v0, 4, v174
	v_cvt_pk_bf16_f32 v3, v4, v5
	v_and_b32_e32 v0, 0xf0, v0
	ds_write_b64 v8, v[2:3]
	v_add_u32_e32 v18, s91, v0
	s_waitcnt lgkmcnt(0)
	v_lshl_add_u32 v6, v170, 8, v18
	ds_read_b128 v[2:5], v6
	v_mul_u32_u24_e32 v0, 0x1400, v170
	v_lshl_add_u64 v[14:15], s[2:3], 0, v[0:1]
	v_lshl_add_u64 v[10:11], v[14:15], 0, v[144:145]
	v_lshl_add_u32 v0, v147, 8, v18
	v_mov_b32_e32 v147, v1
	s_waitcnt lgkmcnt(0)
	global_store_dwordx4 v[10:11], v[2:5], off
	v_lshl_add_u64 v[10:11], v[14:15], 0, v[146:147]
	ds_read_b128 v[6:9], v6 offset:4096
	ds_read_b128 v[2:5], v0
	v_add_co_u32_e32 v16, vcc, s86, v10
	v_lshl_add_u32 v0, v149, 8, v18
	s_nop 0
	v_addc_co_u32_e32 v17, vcc, 0, v11, vcc
	ds_read_b128 v[10:13], v0
	v_lshl_add_u64 v[14:15], v[14:15], 0, s[48:49]
	v_mov_b32_e32 v149, v1
	s_waitcnt lgkmcnt(0)
	global_store_dwordx4 v[16:17], v[2:5], off
	v_lshl_add_u32 v0, v153, 8, v18
	v_mov_b32_e32 v153, v1
	v_lshl_add_u64 v[2:3], v[14:15], 0, v[148:149]
	global_store_dwordx4 v[2:3], v[10:13], off
	ds_read_b128 v[2:5], v0
	v_lshl_add_u32 v0, v151, 8, v18
	v_lshl_add_u64 v[10:11], v[14:15], 0, v[152:153]
	v_add_co_u32_e32 v14, vcc, s86, v10
	v_mov_b32_e32 v151, v1
	s_nop 0
	v_addc_co_u32_e32 v15, vcc, 0, v11, vcc
	ds_read_b128 v[10:13], v0
	v_mad_u32_u24 v0, v170, s85, v196
	s_waitcnt lgkmcnt(0)
	global_store_dwordx4 v[14:15], v[2:5], off
	s_nop 1
	v_lshl_add_u64 v[2:3], s[2:3], 0, v[0:1]
	v_lshl_add_u64 v[2:3], v[2:3], 0, v[144:145]
	v_mad_u32_u24 v0, v170, s85, v197
	global_store_dwordx4 v[2:3], v[6:9], off
	v_lshl_add_u64 v[2:3], s[2:3], 0, v[0:1]
	v_lshl_add_u64 v[2:3], v[2:3], 0, v[150:151]
	v_lshl_add_u32 v0, v155, 8, v18
	global_store_dwordx4 v[2:3], v[10:13], off
	ds_read_b128 v[2:5], v0
	v_mad_u32_u24 v0, v170, s85, v198
	v_lshl_add_u64 v[6:7], s[2:3], 0, v[0:1]
	v_mov_b32_e32 v155, v1
	v_lshl_add_u32 v0, v157, 8, v18
	v_lshl_add_u64 v[10:11], v[6:7], 0, v[154:155]
	ds_read_b128 v[6:9], v0
	v_mad_u32_u24 v0, v170, s85, v199
	s_waitcnt lgkmcnt(0)
	global_store_dwordx4 v[10:11], v[2:5], off
	v_mov_b32_e32 v157, v1
	s_nop 0
	v_lshl_add_u64 v[2:3], s[2:3], 0, v[0:1]
	v_lshl_add_u64 v[2:3], v[2:3], 0, v[156:157]
	global_store_dwordx4 v[2:3], v[6:9], off
	s_waitcnt lgkmcnt(0)
	s_mov_b64 s[2:3], 0

.LBB0_322:
	s_waitcnt vmcnt(0)
	s_mov_b64 s[100:101], exec
	s_mov_b64 exec, s[4:5]
	ds_write_b32 v173, v171 offset:4
	s_mov_b64 exec, s[100:101]
	s_waitcnt lgkmcnt(0)
	s_cmp_ge_i32 s66, s95
	s_cselect_b64 s[54:55], -1, 0
	s_and_b64 vcc, exec, s[54:55]
	s_waitcnt lgkmcnt(0)
	s_barrier
	s_cbranch_vccnz .Lpf_in_3
	s_add_i32 s0, s20, 0x4000
	s_and_b32 s0, s0, 0x4000
	s_add_i32 s0, s0, 0
	s_add_i32 s1, s0, s93
	v_lshl_add_u64 v[2:3], v[148:149], 0, s[2:3]
	s_mov_b32 m0, s1
	s_add_i32 s0, s0, s94
	global_load_lds_dwordx4 v[2:3], off
	v_lshl_add_u64 v[2:3], v[150:151], 0, s[2:3]
	s_add_i32 m0, s1, 0x8000
	s_nop 0
	global_load_lds_dwordx4 v[2:3], off
	v_lshl_add_u64 v[2:3], v[144:145], 0, s[2:3]
	s_mov_b32 m0, s0
	s_nop 0
	global_load_lds_dwordx4 v[2:3], off
	v_lshl_add_u64 v[2:3], v[146:147], 0, s[2:3]
	s_add_i32 m0, s0, 0x8000
	s_nop 0
	global_load_lds_dwordx4 v[2:3], off
	s_branch .LBB0_324

.Lpf_done_3:
.LBB0_324:
	s_cmp_le_i32 s52, s97
	s_cselect_b64 s[0:1], -1, 0
	s_add_i32 s53, s52, 63
	s_cmp_ge_i32 s53, s96
	s_cselect_b64 s[56:57], -1, 0
	s_and_b64 s[0:1], s[0:1], s[56:57]
	s_lshr_b32 s53, s52, s60
	s_cmp_eq_u32 s53, s76
	s_cselect_b64 s[56:57], -1, 0
	s_and_b64 s[0:1], s[0:1], s[56:57]
	s_andn2_b64 vcc, exec, s[0:1]
	s_cbranch_vccnz .LBB0_392
	s_and_b32 s53, s20, 0x4000
	v_add_u32_e32 v0, s53, v159
	v_add_u32_e32 v14, v0, v162
	ds_read_b128 v[2:5], v14
	ds_read_b128 v[6:9], v14 offset:8192
	v_add_u32_e32 v15, v0, v163
	ds_read_b128 v[10:13], v15
	ds_read_b128 v[246:249], v15 offset:8192
	s_waitcnt lgkmcnt(3)
	v_mfma_f32_32x32x16_bf16 v[96:111], v[2:5], v[112:115], 0
	v_add_u32_e32 v14, v0, v164
	ds_read_b128 v[250:253], v14
	s_waitcnt lgkmcnt(3)
	v_mfma_f32_32x32x16_bf16 v[80:95], v[6:9], v[112:115], 0
	ds_read_b128 v[2:5], v14 offset:8192
	s_waitcnt lgkmcnt(3)
	v_mfma_f32_32x32x16_bf16 v[96:111], v[10:13], v[116:119], v[96:111]
	v_add_u32_e32 v15, v0, v165
	ds_read_b128 v[6:9], v15
	s_waitcnt lgkmcnt(3)
	v_mfma_f32_32x32x16_bf16 v[80:95], v[246:249], v[116:119], v[80:95]
	ds_read_b128 v[10:13], v15 offset:8192
	s_waitcnt lgkmcnt(3)
	v_mfma_f32_32x32x16_bf16 v[96:111], v[250:253], v[120:123], v[96:111]
	v_add_u32_e32 v14, v0, v166
	ds_read_b128 v[246:249], v14
	s_waitcnt lgkmcnt(3)
	v_mfma_f32_32x32x16_bf16 v[80:95], v[2:5], v[120:123], v[80:95]
	ds_read_b128 v[250:253], v14 offset:8192
	s_waitcnt lgkmcnt(3)
	v_mfma_f32_32x32x16_bf16 v[96:111], v[6:9], v[124:127], v[96:111]
	v_add_u32_e32 v15, v0, v167
	ds_read_b128 v[2:5], v15
	s_waitcnt lgkmcnt(3)
	v_mfma_f32_32x32x16_bf16 v[80:95], v[10:13], v[124:127], v[80:95]
	ds_read_b128 v[6:9], v15 offset:8192
	s_waitcnt lgkmcnt(3)
	v_mfma_f32_32x32x16_bf16 v[96:111], v[246:249], v[128:131], v[96:111]
	v_add_u32_e32 v14, v0, v168
	ds_read_b128 v[10:13], v14
	s_waitcnt lgkmcnt(3)
	v_mfma_f32_32x32x16_bf16 v[80:95], v[250:253], v[128:131], v[80:95]
	ds_read_b128 v[246:249], v14 offset:8192
	s_waitcnt lgkmcnt(3)
	v_mfma_f32_32x32x16_bf16 v[96:111], v[2:5], v[132:135], v[96:111]
	v_add_u32_e32 v15, v0, v169
	ds_read_b128 v[250:253], v15
	s_waitcnt lgkmcnt(3)
	v_mfma_f32_32x32x16_bf16 v[80:95], v[6:9], v[132:135], v[80:95]
	ds_read_b128 v[2:5], v15 offset:8192
	s_waitcnt lgkmcnt(3)
	v_mfma_f32_32x32x16_bf16 v[96:111], v[10:13], v[136:139], v[96:111]
	s_waitcnt lgkmcnt(2)
	v_mfma_f32_32x32x16_bf16 v[80:95], v[246:249], v[136:139], v[80:95]
	s_waitcnt lgkmcnt(1)
	v_mfma_f32_32x32x16_bf16 v[96:111], v[250:253], v[140:143], v[96:111]
	s_waitcnt lgkmcnt(0)
	v_mfma_f32_32x32x16_bf16 v[80:95], v[2:5], v[140:143], v[80:95]
	s_nop 7
	s_nop 3
	v_add_u32_e32 v0, 59, v182
	v_subrev_u32_e32 v246, 0, v0
	v_subrev_u32_e32 v247, 1, v0
	v_subrev_u32_e32 v248, 2, v0
	v_cmp_ge_u32_e64 vcc, v254, v246
	v_cmp_ge_u32_e64 s[0:1], v254, v247
	v_cmp_ge_u32_e64 s[56:57], v254, v248
	v_cndmask_b32_e64 v13, v195, v96, vcc
	v_cndmask_b32_e64 v97, v195, v97, s[0:1]
	v_cndmask_b32_e64 v14, v195, v98, s[56:57]
	v_subrev_u32_e32 v246, 3, v0
	v_subrev_u32_e32 v247, 8, v0
	v_subrev_u32_e32 v248, 9, v0
	v_cmp_ge_u32_e64 vcc, v254, v246
	v_cmp_ge_u32_e64 s[0:1], v254, v247
	v_cmp_ge_u32_e64 s[56:57], v254, v248
	v_cndmask_b32_e64 v98, v195, v99, vcc
	v_cndmask_b32_e64 v11, v195, v100, s[0:1]
	v_cndmask_b32_e64 v15, v195, v101, s[56:57]
	v_subrev_u32_e32 v246, 10, v0
	v_subrev_u32_e32 v247, 11, v0
	v_subrev_u32_e32 v248, 16, v0
	v_cmp_ge_u32_e64 vcc, v254, v246
	v_cmp_ge_u32_e64 s[0:1], v254, v247
	v_cmp_ge_u32_e64 s[56:57], v254, v248
	v_cndmask_b32_e64 v9, v195, v102, vcc
	v_cndmask_b32_e64 v12, v195, v103, s[0:1]
	v_cndmask_b32_e64 v7, v195, v104, s[56:57]
	v_subrev_u32_e32 v246, 17, v0
	v_subrev_u32_e32 v247, 18, v0
	v_subrev_u32_e32 v248, 19, v0
	v_cmp_ge_u32_e64 vcc, v254, v246
	v_cmp_ge_u32_e64 s[0:1], v254, v247
	v_cmp_ge_u32_e64 s[56:57], v254, v248
	v_cndmask_b32_e64 v10, v195, v105, vcc
	v_cndmask_b32_e64 v5, v195, v106, s[0:1]
	v_cndmask_b32_e64 v8, v195, v107, s[56:57]
	v_subrev_u32_e32 v246, 24, v0
	v_subrev_u32_e32 v247, 25, v0
	v_subrev_u32_e32 v248, 26, v0
	v_cmp_ge_u32_e64 vcc, v254, v246
	v_cmp_ge_u32_e64 s[0:1], v254, v247
	v_cmp_ge_u32_e64 s[56:57], v254, v248
	v_cndmask_b32_e64 v3, v195, v108, vcc
	v_cndmask_b32_e64 v6, v195, v109, s[0:1]
	v_cndmask_b32_e64 v2, v195, v110, s[56:57]
	v_subrev_u32_e32 v246, 27, v0
	v_subrev_u32_e32 v247, 32, v0
	v_subrev_u32_e32 v248, 33, v0
	v_cmp_ge_u32_e64 vcc, v254, v246
	v_cmp_ge_u32_e64 s[0:1], v254, v247
	v_cmp_ge_u32_e64 s[56:57], v254, v248
	v_cndmask_b32_e64 v4, v195, v111, vcc
	v_cndmask_b32_e64 v80, v195, v80, s[0:1]
	v_cndmask_b32_e64 v81, v195, v81, s[56:57]
	v_subrev_u32_e32 v246, 34, v0
	v_subrev_u32_e32 v247, 35, v0
	v_subrev_u32_e32 v248, 40, v0
	v_cmp_ge_u32_e64 vcc, v254, v246
	v_cmp_ge_u32_e64 s[0:1], v254, v247
	v_cmp_ge_u32_e64 s[56:57], v254, v248
	v_cndmask_b32_e64 v82, v195, v82, vcc
	v_cndmask_b32_e64 v83, v195, v83, s[0:1]
	v_cndmask_b32_e64 v84, v195, v84, s[56:57]
	v_subrev_u32_e32 v246, 41, v0
	v_subrev_u32_e32 v247, 42, v0
	v_subrev_u32_e32 v248, 43, v0
	v_cmp_ge_u32_e64 vcc, v254, v246
	v_cmp_ge_u32_e64 s[0:1], v254, v247
	v_cmp_ge_u32_e64 s[56:57], v254, v248
	v_cndmask_b32_e64 v85, v195, v85, vcc
	v_cndmask_b32_e64 v86, v195, v86, s[0:1]
	v_cndmask_b32_e64 v87, v195, v87, s[56:57]
	v_subrev_u32_e32 v246, 48, v0
	v_subrev_u32_e32 v247, 49, v0
	v_subrev_u32_e32 v248, 50, v0
	v_cmp_ge_u32_e64 vcc, v254, v246
	v_cmp_ge_u32_e64 s[0:1], v254, v247
	v_cmp_ge_u32_e64 s[56:57], v254, v248
	v_cndmask_b32_e64 v88, v195, v88, vcc
	v_cndmask_b32_e64 v89, v195, v89, s[0:1]
	v_cndmask_b32_e64 v90, v195, v90, s[56:57]
	v_subrev_u32_e32 v246, 51, v0
	v_subrev_u32_e32 v247, 56, v0
	v_subrev_u32_e32 v248, 57, v0
	v_cmp_ge_u32_e64 vcc, v254, v246
	v_cmp_ge_u32_e64 s[0:1], v254, v247
	v_cmp_ge_u32_e64 s[56:57], v254, v248
	v_cndmask_b32_e64 v91, v195, v91, vcc
	v_cndmask_b32_e64 v92, v195, v92, s[0:1]
	v_cndmask_b32_e64 v93, v195, v93, s[56:57]
	v_subrev_u32_e32 v246, 58, v0
	v_subrev_u32_e32 v247, 59, v0
	v_cmp_ge_u32_e64 vcc, v254, v246
	v_cmp_ge_u32_e64 s[0:1], v254, v247
	s_nop 1
	v_cndmask_b32_e64 v94, v195, v94, vcc
	v_cndmask_b32_e64 v95, v195, v95, s[0:1]
	s_setprio 1
	v_max_f32_e32 v0, v13, v13
	v_max_f32_e32 v96, v97, v97
	v_max_f32_e32 v0, v0, v96
	v_max3_f32 v0, v0, v14, v98
	v_max3_f32 v0, v0, v11, v15
	v_max3_f32 v0, v0, v9, v12
	v_max3_f32 v0, v0, v7, v10
	v_max3_f32 v0, v0, v5, v8
	v_max3_f32 v0, v0, v3, v6
	v_max3_f32 v0, v0, v2, v4
	v_max3_f32 v0, v0, v80, v81
	v_max3_f32 v0, v0, v82, v83
	v_max3_f32 v0, v0, v84, v85
	v_max3_f32 v0, v0, v86, v87
	v_max3_f32 v0, v0, v88, v89
	v_max3_f32 v0, v0, v90, v91
	v_max3_f32 v0, v0, v92, v93
	v_max3_f32 v0, v0, v94, v95
	v_mov_b32_e32 v96, v0
	s_nop 1
	v_permlane32_swap_b32_e32 v0, v96
	v_max3_f32 v96, v184, v0, v96
	v_sub_f32_e32 v0, v184, v96
	v_exp_f32_e32 v0, v0
	s_nop 0
	v_cmp_neq_f32_e32 vcc, 1.0, v0
	s_cbranch_vccz .LBB0_391
	v_pk_mul_f32 v[78:79], v[78:79], v[0:1] op_sel_hi:[1,0]
	v_pk_mul_f32 v[76:77], v[76:77], v[0:1] op_sel_hi:[1,0]
	v_pk_mul_f32 v[74:75], v[74:75], v[0:1] op_sel_hi:[1,0]
	v_pk_mul_f32 v[72:73], v[72:73], v[0:1] op_sel_hi:[1,0]
	v_pk_mul_f32 v[70:71], v[70:71], v[0:1] op_sel_hi:[1,0]
	v_pk_mul_f32 v[68:69], v[68:69], v[0:1] op_sel_hi:[1,0]
	v_pk_mul_f32 v[66:67], v[66:67], v[0:1] op_sel_hi:[1,0]
	v_pk_mul_f32 v[64:65], v[64:65], v[0:1] op_sel_hi:[1,0]
	v_pk_mul_f32 v[62:63], v[62:63], v[0:1] op_sel_hi:[1,0]
	v_pk_mul_f32 v[60:61], v[60:61], v[0:1] op_sel_hi:[1,0]
	v_pk_mul_f32 v[58:59], v[58:59], v[0:1] op_sel_hi:[1,0]
	v_pk_mul_f32 v[56:57], v[56:57], v[0:1] op_sel_hi:[1,0]
	v_pk_mul_f32 v[54:55], v[54:55], v[0:1] op_sel_hi:[1,0]
	v_pk_mul_f32 v[52:53], v[52:53], v[0:1] op_sel_hi:[1,0]
	v_pk_mul_f32 v[50:51], v[50:51], v[0:1] op_sel_hi:[1,0]
	v_pk_mul_f32 v[48:49], v[48:49], v[0:1] op_sel_hi:[1,0]
	v_pk_mul_f32 v[46:47], v[46:47], v[0:1] op_sel_hi:[1,0]
	v_pk_mul_f32 v[44:45], v[44:45], v[0:1] op_sel_hi:[1,0]
	v_pk_mul_f32 v[42:43], v[42:43], v[0:1] op_sel_hi:[1,0]
	v_pk_mul_f32 v[40:41], v[40:41], v[0:1] op_sel_hi:[1,0]
	v_pk_mul_f32 v[38:39], v[38:39], v[0:1] op_sel_hi:[1,0]
	v_pk_mul_f32 v[36:37], v[36:37], v[0:1] op_sel_hi:[1,0]
	v_pk_mul_f32 v[34:35], v[34:35], v[0:1] op_sel_hi:[1,0]
	v_pk_mul_f32 v[32:33], v[32:33], v[0:1] op_sel_hi:[1,0]
	v_pk_mul_f32 v[30:31], v[30:31], v[0:1] op_sel_hi:[1,0]
	v_pk_mul_f32 v[28:29], v[28:29], v[0:1] op_sel_hi:[1,0]
	v_pk_mul_f32 v[26:27], v[26:27], v[0:1] op_sel_hi:[1,0]
	v_pk_mul_f32 v[24:25], v[24:25], v[0:1] op_sel_hi:[1,0]
	v_pk_mul_f32 v[22:23], v[22:23], v[0:1] op_sel_hi:[1,0]
	v_pk_mul_f32 v[20:21], v[20:21], v[0:1] op_sel_hi:[1,0]
	v_pk_mul_f32 v[18:19], v[18:19], v[0:1] op_sel_hi:[1,0]
	v_pk_mul_f32 v[16:17], v[16:17], v[0:1] op_sel_hi:[1,0]

.LBB0_397:
	v_mov_b32_e32 v2, v183
	s_nop 1
	v_permlane32_swap_b32_e32 v183, v2
	v_add_f32_e32 v2, v183, v2
	v_div_scale_f32 v3, s[0:1], v2, v2, 1.0
	v_rcp_f32_e32 v4, v3
	s_lshl_b32 s0, s92, 13
	s_add_i32 s0, s0, 0
	v_lshlrev_b32_e32 v0, 3, v156
	v_fma_f32 v5, -v3, v4, 1.0
	v_fmac_f32_e32 v4, v5, v4
	v_div_scale_f32 v5, vcc, 1.0, v2, 1.0
	v_mul_f32_e32 v6, v5, v4
	v_fma_f32 v7, -v3, v6, v5
	v_fmac_f32_e32 v6, v7, v4
	v_fma_f32 v3, -v3, v6, v5
	s_add_i32 s0, s0, 0x10000
	v_div_fmas_f32 v3, v3, v4, v6
	v_div_fixup_f32 v4, v3, v2, 1.0
	v_add3_u32 v0, s0, v81, v0
	v_lshlrev_b32_e32 v3, 4, v157
	v_add_u32_e32 v5, v0, v3
	v_pk_mul_f32 v[6:7], v[64:65], v[4:5] op_sel_hi:[1,0]
	v_pk_mul_f32 v[8:9], v[66:67], v[4:5] op_sel_hi:[1,0]
	v_cvt_pk_bf16_f32 v6, v6, v7
	v_cvt_pk_bf16_f32 v7, v8, v9
	s_waitcnt vmcnt(3)
	ds_write_b64 v5, v[6:7]
	v_xad_u32 v5, v3, 16, v0
	v_pk_mul_f32 v[6:7], v[68:69], v[4:5] op_sel_hi:[1,0]
	v_pk_mul_f32 v[8:9], v[70:71], v[4:5] op_sel_hi:[1,0]
	v_cvt_pk_bf16_f32 v6, v6, v7
	v_cvt_pk_bf16_f32 v7, v8, v9
	ds_write_b64 v5, v[6:7]
	v_xad_u32 v5, v3, 32, v0
	v_pk_mul_f32 v[6:7], v[72:73], v[4:5] op_sel_hi:[1,0]
	v_pk_mul_f32 v[8:9], v[74:75], v[4:5] op_sel_hi:[1,0]
	v_cvt_pk_bf16_f32 v6, v6, v7
	v_cvt_pk_bf16_f32 v7, v8, v9
	ds_write_b64 v5, v[6:7]
	v_xad_u32 v5, v3, 48, v0
	v_pk_mul_f32 v[6:7], v[76:77], v[4:5] op_sel_hi:[1,0]
	v_pk_mul_f32 v[8:9], v[78:79], v[4:5] op_sel_hi:[1,0]
	v_cvt_pk_bf16_f32 v6, v6, v7
	v_cvt_pk_bf16_f32 v7, v8, v9
	ds_write_b64 v5, v[6:7]
	v_xad_u32 v5, v3, 64, v0
	v_pk_mul_f32 v[6:7], v[48:49], v[4:5] op_sel_hi:[1,0]
	v_pk_mul_f32 v[8:9], v[50:51], v[4:5] op_sel_hi:[1,0]
	v_cvt_pk_bf16_f32 v6, v6, v7
	v_cvt_pk_bf16_f32 v7, v8, v9
	ds_write_b64 v5, v[6:7]
	v_xad_u32 v5, v3, s69, v0
	v_pk_mul_f32 v[6:7], v[52:53], v[4:5] op_sel_hi:[1,0]
	v_pk_mul_f32 v[8:9], v[54:55], v[4:5] op_sel_hi:[1,0]
	v_cvt_pk_bf16_f32 v6, v6, v7
	v_cvt_pk_bf16_f32 v7, v8, v9
	ds_write_b64 v5, v[6:7]
	v_xad_u32 v5, v3, s70, v0
	v_pk_mul_f32 v[6:7], v[56:57], v[4:5] op_sel_hi:[1,0]
	v_pk_mul_f32 v[8:9], v[58:59], v[4:5] op_sel_hi:[1,0]
	v_cvt_pk_bf16_f32 v6, v6, v7
	v_cvt_pk_bf16_f32 v7, v8, v9
	ds_write_b64 v5, v[6:7]
	v_xad_u32 v5, v3, s71, v0
	v_pk_mul_f32 v[6:7], v[60:61], v[4:5] op_sel_hi:[1,0]
	v_pk_mul_f32 v[8:9], v[62:63], v[4:5] op_sel_hi:[1,0]
	v_cvt_pk_bf16_f32 v6, v6, v7
	v_cvt_pk_bf16_f32 v7, v8, v9
	ds_write_b64 v5, v[6:7]
	v_xad_u32 v5, v3, s72, v0
	v_pk_mul_f32 v[6:7], v[32:33], v[4:5] op_sel_hi:[1,0]
	v_pk_mul_f32 v[8:9], v[34:35], v[4:5] op_sel_hi:[1,0]
	v_cvt_pk_bf16_f32 v6, v6, v7
	v_cvt_pk_bf16_f32 v7, v8, v9
	ds_write_b64 v5, v[6:7]
	v_xad_u32 v5, v3, s73, v0
	v_pk_mul_f32 v[6:7], v[36:37], v[4:5] op_sel_hi:[1,0]
	v_pk_mul_f32 v[8:9], v[38:39], v[4:5] op_sel_hi:[1,0]
	v_cvt_pk_bf16_f32 v6, v6, v7
	v_cvt_pk_bf16_f32 v7, v8, v9
	ds_write_b64 v5, v[6:7]
	v_xad_u32 v5, v3, s79, v0
	v_pk_mul_f32 v[6:7], v[40:41], v[4:5] op_sel_hi:[1,0]
	v_pk_mul_f32 v[8:9], v[42:43], v[4:5] op_sel_hi:[1,0]
	v_cvt_pk_bf16_f32 v6, v6, v7
	v_cvt_pk_bf16_f32 v7, v8, v9
	ds_write_b64 v5, v[6:7]
	v_xad_u32 v5, v3, s80, v0
	v_pk_mul_f32 v[6:7], v[44:45], v[4:5] op_sel_hi:[1,0]
	v_pk_mul_f32 v[8:9], v[46:47], v[4:5] op_sel_hi:[1,0]
	v_cvt_pk_bf16_f32 v6, v6, v7
	v_cvt_pk_bf16_f32 v7, v8, v9
	ds_write_b64 v5, v[6:7]
	v_xad_u32 v5, v3, s81, v0
	v_pk_mul_f32 v[6:7], v[16:17], v[4:5] op_sel_hi:[1,0]
	v_pk_mul_f32 v[8:9], v[18:19], v[4:5] op_sel_hi:[1,0]
	v_cvt_pk_bf16_f32 v6, v6, v7
	v_cvt_pk_bf16_f32 v7, v8, v9
	ds_write_b64 v5, v[6:7]
	v_xad_u32 v5, v3, s82, v0
	v_pk_mul_f32 v[6:7], v[20:21], v[4:5] op_sel_hi:[1,0]
	v_pk_mul_f32 v[8:9], v[22:23], v[4:5] op_sel_hi:[1,0]
	v_cvt_pk_bf16_f32 v6, v6, v7
	v_cvt_pk_bf16_f32 v7, v8, v9
	ds_write_b64 v5, v[6:7]
	v_xad_u32 v5, v3, s83, v0
	v_pk_mul_f32 v[6:7], v[24:25], v[4:5] op_sel_hi:[1,0]
	v_pk_mul_f32 v[8:9], v[26:27], v[4:5] op_sel_hi:[1,0]
	v_cvt_pk_bf16_f32 v6, v6, v7
	v_cvt_pk_bf16_f32 v7, v8, v9
	ds_write_b64 v5, v[6:7]
	v_pk_mul_f32 v[6:7], v[28:29], v[4:5] op_sel_hi:[1,0]
	v_pk_mul_f32 v[4:5], v[30:31], v[4:5] op_sel_hi:[1,0]
	v_xad_u32 v0, v3, s84, v0
	v_cvt_pk_bf16_f32 v6, v6, v7
	v_cvt_pk_bf16_f32 v7, v4, v5
	ds_write_b64 v0, v[6:7]
	v_lshlrev_b32_e32 v0, 4, v152
	v_and_b32_e32 v0, 0xf0, v0
	v_add_u32_e32 v3, s0, v0
	v_add_u32_e32 v0, v80, v153
	v_ashrrev_i32_e32 v4, s60, v0
	v_lshlrev_b32_e32 v0, s59, v0
	v_and_b32_e32 v0, 0x7ff, v0
	s_lshl_b32 s0, s61, 14
	v_add_u32_e32 v8, v0, v4
	s_waitcnt lgkmcnt(0)
	s_or_b32 s20, s91, s0
	v_ashrrev_i32_e32 v9, 31, v8
	v_lshl_add_u32 v0, v153, 8, v3
	ds_read_b128 v[4:7], v0
	v_lshl_add_u64 v[8:9], v[8:9], 0, s[20:21]
	v_lshlrev_b64 v[8:9], 10, v[8:9]
	v_xor_b32_e32 v0, v153, v152
	v_lshl_add_u64 v[8:9], s[46:47], 0, v[8:9]
	s_lshl_b32 s0, s90, 1
	s_mov_b32 s1, s21
	v_lshlrev_b32_e32 v0, 4, v0
	v_lshl_add_u64 v[8:9], v[8:9], 0, s[0:1]
	v_and_b32_e32 v0, 0xf0, v0
	v_lshl_add_u64 v[12:13], v[8:9], 0, v[0:1]
	v_or_b32_e32 v14, 4, v153
	s_waitcnt lgkmcnt(0)
	global_store_dwordx4 v[12:13], v[4:7], off
	v_lshl_add_u32 v8, v14, 8, v3
	ds_read_b128 v[8:11], v8
	v_add_u32_e32 v4, v80, v14
	v_ashrrev_i32_e32 v5, s60, v4
	v_lshlrev_b32_e32 v4, s59, v4
	v_and_b32_e32 v4, 0x7ff, v4
	v_add_u32_e32 v4, v4, v5
	v_ashrrev_i32_e32 v5, 31, v4
	v_lshl_add_u64 v[4:5], v[4:5], 0, s[20:21]
	v_lshlrev_b64 v[4:5], 10, v[4:5]
	v_bitop3_b32 v6, v153, v152, 4 bitop3:0x36
	v_lshl_add_u64 v[4:5], s[46:47], 0, v[4:5]
	v_lshlrev_b32_e32 v6, 4, v6
	v_lshl_add_u64 v[4:5], v[4:5], 0, s[0:1]
	v_and_b32_e32 v6, 0xf0, v6
	v_mov_b32_e32 v7, v1
	v_lshl_add_u64 v[4:5], v[4:5], 0, v[6:7]
	s_waitcnt lgkmcnt(0)
	global_store_dwordx4 v[4:5], v[8:11], off
	v_or_b32_e32 v4, 8, v153
	v_add_u32_e32 v5, v80, v4
	v_ashrrev_i32_e32 v6, s60, v5
	v_lshlrev_b32_e32 v5, s59, v5
	v_and_b32_e32 v5, 0x7ff, v5
	v_add_u32_e32 v8, v5, v6
	v_ashrrev_i32_e32 v9, 31, v8
	v_lshl_add_u32 v4, v4, 8, v3
	ds_read_b128 v[4:7], v4
	v_lshl_add_u64 v[8:9], v[8:9], 0, s[20:21]
	v_lshlrev_b64 v[8:9], 10, v[8:9]
	v_bitop3_b32 v10, v153, v152, 8 bitop3:0x36
	v_lshl_add_u64 v[8:9], s[46:47], 0, v[8:9]
	v_lshlrev_b32_e32 v10, 4, v10
	v_lshl_add_u64 v[8:9], v[8:9], 0, s[0:1]
	v_and_b32_e32 v10, 0xf0, v10
	v_mov_b32_e32 v11, v1
	v_or_b32_e32 v14, 12, v153
	v_lshl_add_u64 v[12:13], v[8:9], 0, v[10:11]
	v_lshl_add_u32 v8, v14, 8, v3
	ds_read_b128 v[8:11], v8
	s_waitcnt lgkmcnt(0)
	global_store_dwordx4 v[12:13], v[4:7], off
	v_cmp_gt_u32_e32 vcc, 32, v152
	s_nop 0
	v_add_u32_e32 v4, v80, v14
	v_ashrrev_i32_e32 v5, s60, v4
	v_lshlrev_b32_e32 v4, s59, v4
	v_and_b32_e32 v4, 0x7ff, v4
	v_add_u32_e32 v4, v4, v5
	v_ashrrev_i32_e32 v5, 31, v4
	v_lshl_add_u64 v[4:5], v[4:5], 0, s[20:21]
	v_lshlrev_b64 v[4:5], 10, v[4:5]
	v_bitop3_b32 v6, v153, v152, 12 bitop3:0x36
	v_lshl_add_u64 v[4:5], s[46:47], 0, v[4:5]
	v_lshlrev_b32_e32 v6, 4, v6
	v_lshl_add_u64 v[4:5], v[4:5], 0, s[0:1]
	v_and_b32_e32 v6, 0xf0, v6
	v_mov_b32_e32 v7, v1
	v_lshl_add_u64 v[4:5], v[4:5], 0, v[6:7]
	global_store_dwordx4 v[4:5], v[8:11], off
	v_or_b32_e32 v4, 16, v153
	v_add_u32_e32 v5, v80, v4
	v_ashrrev_i32_e32 v6, s60, v5
	v_lshlrev_b32_e32 v5, s59, v5
	v_and_b32_e32 v5, 0x7ff, v5
	v_add_u32_e32 v8, v5, v6
	v_ashrrev_i32_e32 v9, 31, v8
	v_lshl_add_u32 v4, v4, 8, v3
	v_lshl_add_u64 v[8:9], v[8:9], 0, s[20:21]
	ds_read_b128 v[4:7], v4
	v_lshlrev_b64 v[8:9], 10, v[8:9]
	v_lshl_add_u64 v[8:9], s[46:47], 0, v[8:9]
	v_lshl_add_u64 v[8:9], v[8:9], 0, s[0:1]
	v_lshl_add_u64 v[12:13], v[8:9], 0, v[0:1]
	v_or_b32_e32 v0, 20, v153
	v_lshl_add_u32 v8, v0, 8, v3
	v_add_u32_e32 v0, v80, v0
	ds_read_b128 v[8:11], v8
	s_waitcnt lgkmcnt(0)
	global_store_dwordx4 v[12:13], v[4:7], off
	s_nop 1
	v_ashrrev_i32_e32 v4, s60, v0
	v_lshlrev_b32_e32 v0, s59, v0
	v_and_b32_e32 v0, 0x7ff, v0
	v_add_u32_e32 v4, v0, v4
	v_ashrrev_i32_e32 v5, 31, v4
	v_lshl_add_u64 v[4:5], v[4:5], 0, s[20:21]
	v_lshlrev_b64 v[4:5], 10, v[4:5]
	v_bitop3_b32 v0, v153, v152, 20 bitop3:0x36
	v_lshl_add_u64 v[4:5], s[46:47], 0, v[4:5]
	v_lshlrev_b32_e32 v0, 4, v0
	v_lshl_add_u64 v[4:5], v[4:5], 0, s[0:1]
	v_and_b32_e32 v0, 0xf0, v0
	v_lshl_add_u64 v[4:5], v[4:5], 0, v[0:1]
	v_or_b32_e32 v0, 24, v153
	global_store_dwordx4 v[4:5], v[8:11], off
	v_add_u32_e32 v4, v80, v0
	v_ashrrev_i32_e32 v5, s60, v4
	v_lshlrev_b32_e32 v4, s59, v4
	v_and_b32_e32 v4, 0x7ff, v4
	v_add_u32_e32 v8, v4, v5
	v_ashrrev_i32_e32 v9, 31, v8
	v_lshl_add_u32 v0, v0, 8, v3
	v_lshl_add_u64 v[8:9], v[8:9], 0, s[20:21]
	ds_read_b128 v[4:7], v0
	v_lshlrev_b64 v[8:9], 10, v[8:9]
	v_bitop3_b32 v0, v153, v152, 24 bitop3:0x36
	v_lshl_add_u64 v[8:9], s[46:47], 0, v[8:9]
	v_lshlrev_b32_e32 v0, 4, v0
	v_lshl_add_u64 v[8:9], v[8:9], 0, s[0:1]
	v_and_b32_e32 v0, 0xf0, v0
	v_lshl_add_u64 v[12:13], v[8:9], 0, v[0:1]
	v_or_b32_e32 v0, 28, v153
	v_lshl_add_u32 v3, v0, 8, v3
	v_add_u32_e32 v0, v80, v0
	ds_read_b128 v[8:11], v3
	v_ashrrev_i32_e32 v3, s60, v0
	v_lshlrev_b32_e32 v0, s59, v0
	v_and_b32_e32 v0, 0x7ff, v0
	s_waitcnt lgkmcnt(0)
	global_store_dwordx4 v[12:13], v[4:7], off
	s_nop 1
	v_add_u32_e32 v4, v0, v3
	v_ashrrev_i32_e32 v5, 31, v4
	v_lshl_add_u64 v[4:5], v[4:5], 0, s[20:21]
	v_lshlrev_b64 v[4:5], 10, v[4:5]
	v_bitop3_b32 v0, v153, v152, 28 bitop3:0x36
	v_lshl_add_u64 v[4:5], s[46:47], 0, v[4:5]
	v_lshlrev_b32_e32 v0, 4, v0
	v_lshl_add_u64 v[4:5], v[4:5], 0, s[0:1]
	v_and_b32_e32 v0, 0xf0, v0
	v_lshl_add_u64 v[4:5], v[4:5], 0, v[0:1]
	global_store_dwordx4 v[4:5], v[8:11], off
	s_and_saveexec_b64 s[0:1], vcc
	s_cbranch_execz .LBB0_399
	v_lshlrev_b32_e32 v0, s59, v155
	v_and_b32_e32 v0, 0x7ff, v0
	v_log_f32_e32 v4, v2
	v_add_u32_e32 v2, v0, v154
	v_ashrrev_i32_e32 v3, 31, v2
	v_lshl_add_u64 v[2:3], v[2:3], 0, s[20:21]
	v_lshl_add_u64 v[2:3], v[2:3], 4, s[12:13]
	s_lshl_b32 s20, s58, 2
	v_add_f32_e32 v0, v96, v4
	v_lshl_add_u64 v[2:3], v[2:3], 0, s[20:21]
	global_store_dword v[2:3], v0, off

.LBB0_424:
	s_waitcnt vmcnt(0)
	s_mov_b64 s[100:101], exec
	s_mov_b64 exec, s[4:5]
	ds_write_b32 v173, v171 offset:4
	s_mov_b64 exec, s[100:101]
	s_waitcnt lgkmcnt(0)
	s_add_i32 s58, s59, 1
	s_cmp_ge_u32 s58, s56
	s_barrier
	s_cbranch_scc1 .Lpf_in_1
	s_cmp_lt_u32 s59, 3
	s_cselect_b32 s0, s20, 0xffffff00
	s_add_i32 s0, s0, s57
	s_add_i32 s0, s0, 64
	s_ashr_i32 s1, s0, 31
	s_add_i32 s2, s55, 0x4000
	s_and_b32 s52, s2, 0x4000
	v_lshl_add_u64 v[2:3], s[0:1], 0, v[158:159]
	v_mad_u64_u32 v[4:5], s[2:3], v2, s62, v[162:163]
	s_add_i32 s52, s52, 0
	v_mad_i32_i24 v5, v3, s62, v5
	s_add_i32 s53, s52, s92
	v_lshl_add_u64 v[4:5], v[4:5], 0, s[24:25]
	s_mov_b32 m0, s53
	s_nop 0
	global_load_lds_dwordx4 v[4:5], off
	v_mad_u64_u32 v[4:5], s[2:3], v2, s62, v[164:165]
	v_mad_i32_i24 v5, v3, s62, v5
	s_add_i32 m0, s53, 0x8000
	v_lshl_add_u64 v[2:3], s[0:1], 0, v[160:161]
	global_load_lds_dwordx4 v[4:5], off
	v_mad_u64_u32 v[4:5], s[0:1], v2, s62, v[166:167]
	v_mad_i32_i24 v5, v3, s62, v5
	s_add_i32 s2, s52, s93
	v_lshl_add_u64 v[4:5], v[4:5], 0, s[24:25]
	s_mov_b32 m0, s2
	s_nop 0
	global_load_lds_dwordx4 v[4:5], off
	v_mad_u64_u32 v[4:5], s[0:1], v2, s62, v[168:169]
	v_mad_i32_i24 v5, v3, s62, v5
	s_add_i32 m0, s2, 0x8000
	s_nop 0
	global_load_lds_dwordx4 v[4:5], off
	s_branch .LBB0_426

.Lpf_done_1:
.LBB0_426:
	s_cmp_lt_u32 s59, 4
	s_cselect_b64 s[0:1], -1, 0
	s_cmp_gt_u32 s59, 3
	s_mov_b64 s[52:53], -1
	s_cbranch_scc0 .LBB0_429
	s_add_i32 s2, s59, -4
	s_lshr_b32 s2, s2, 2
	v_lshrrev_b32_e32 v0, s2, v177
	v_bfe_u32 v2, v177, s2, 1
	v_and_b32_e32 v0, 1, v0
	v_cmp_ne_u32_e32 vcc, 0, v2
	s_cmp_eq_u64 vcc, 0
	v_cmp_eq_u32_e32 vcc, 1, v0
	s_cselect_b64 s[2:3], -1, 0
	s_nop 0
	v_cndmask_b32_e64 v80, v195, 0, vcc
	s_cbranch_execz .LBB0_430

.LBB0_436:
	v_mov_b32_e32 v0, v212
	s_nop 1
	v_permlane32_swap_b32_e32 v212, v0
	v_add_f32_e32 v0, v212, v0
	v_div_scale_f32 v2, s[0:1], v0, v0, 1.0
	v_rcp_f32_e32 v4, v2
	v_add3_u32 v8, s61, v178, v176
	v_lshlrev_b32_e32 v9, 4, v145
	s_waitcnt vmcnt(3)
	v_fma_f32 v3, -v2, v4, 1.0
	v_fmac_f32_e32 v4, v3, v4
	v_div_scale_f32 v3, vcc, 1.0, v0, 1.0
	v_mul_f32_e32 v5, v3, v4
	v_fma_f32 v6, -v2, v5, v3
	v_fmac_f32_e32 v5, v6, v4
	v_add_u32_e32 v10, v8, v9
	v_fma_f32 v6, -v2, v5, v3
	ds_read_b64 v[2:3], v10
	v_div_fmas_f32 v4, v6, v4, v5
	v_div_fixup_f32 v0, v4, v0, 1.0
	v_pk_mul_f32 v[4:5], v[64:65], v[0:1] op_sel_hi:[1,0]
	s_mulk_i32 s91, 0x1400
	s_waitcnt lgkmcnt(0)
	v_lshlrev_b32_e32 v6, 16, v2
	v_and_b32_e32 v7, 0xffff0000, v2
	v_pk_mul_f32 v[4:5], v[4:5], v[6:7]
	v_lshlrev_b32_e32 v6, 16, v3
	v_cvt_pk_bf16_f32 v2, v4, v5
	v_pk_mul_f32 v[4:5], v[66:67], v[0:1] op_sel_hi:[1,0]
	v_and_b32_e32 v7, 0xffff0000, v3
	v_pk_mul_f32 v[4:5], v[4:5], v[6:7]
	s_mul_hi_u32 s0, s90, 0x1400
	v_cvt_pk_bf16_f32 v3, v4, v5
	ds_write_b64 v10, v[2:3]
	v_xad_u32 v10, v9, 16, v8
	ds_read_b64 v[2:3], v10
	v_pk_mul_f32 v[4:5], v[68:69], v[0:1] op_sel_hi:[1,0]
	s_add_i32 s0, s0, s91
	s_mulk_i32 s90, 0x1400
	s_add_u32 s1, s30, s90
	s_waitcnt lgkmcnt(0)
	v_lshlrev_b32_e32 v6, 16, v2
	v_and_b32_e32 v7, 0xffff0000, v2
	v_pk_mul_f32 v[4:5], v[4:5], v[6:7]
	v_lshlrev_b32_e32 v6, 16, v3
	v_cvt_pk_bf16_f32 v2, v4, v5
	v_pk_mul_f32 v[4:5], v[70:71], v[0:1] op_sel_hi:[1,0]
	v_and_b32_e32 v7, 0xffff0000, v3
	v_pk_mul_f32 v[4:5], v[4:5], v[6:7]
	s_addc_u32 s2, s31, s0
	v_cvt_pk_bf16_f32 v3, v4, v5
	ds_write_b64 v10, v[2:3]
	v_xad_u32 v10, v9, 32, v8
	ds_read_b64 v[2:3], v10
	v_pk_mul_f32 v[4:5], v[72:73], v[0:1] op_sel_hi:[1,0]
	s_add_u32 s0, s1, s60
	s_addc_u32 s1, s2, 0
	v_mov_b32_e32 v145, v1
	s_waitcnt lgkmcnt(0)
	v_lshlrev_b32_e32 v6, 16, v2
	v_and_b32_e32 v7, 0xffff0000, v2
	v_pk_mul_f32 v[4:5], v[4:5], v[6:7]
	v_lshlrev_b32_e32 v6, 16, v3
	v_cvt_pk_bf16_f32 v2, v4, v5
	v_pk_mul_f32 v[4:5], v[74:75], v[0:1] op_sel_hi:[1,0]
	v_and_b32_e32 v7, 0xffff0000, v3
	v_pk_mul_f32 v[4:5], v[4:5], v[6:7]
	s_mov_b64 s[2:3], s[22:23]
	v_cvt_pk_bf16_f32 v3, v4, v5
	ds_write_b64 v10, v[2:3]
	v_xad_u32 v10, v9, 48, v8
	ds_read_b64 v[2:3], v10
	v_pk_mul_f32 v[4:5], v[76:77], v[0:1] op_sel_hi:[1,0]
	s_waitcnt lgkmcnt(0)
	v_lshlrev_b32_e32 v6, 16, v2
	v_and_b32_e32 v7, 0xffff0000, v2
	v_pk_mul_f32 v[4:5], v[4:5], v[6:7]
	v_lshlrev_b32_e32 v6, 16, v3
	v_cvt_pk_bf16_f32 v2, v4, v5
	v_pk_mul_f32 v[4:5], v[78:79], v[0:1] op_sel_hi:[1,0]
	v_and_b32_e32 v7, 0xffff0000, v3
	v_pk_mul_f32 v[4:5], v[4:5], v[6:7]
	s_nop 0
	v_cvt_pk_bf16_f32 v3, v4, v5
	ds_write_b64 v10, v[2:3]
	v_xad_u32 v10, v9, 64, v8
	ds_read_b64 v[2:3], v10
	v_pk_mul_f32 v[4:5], v[48:49], v[0:1] op_sel_hi:[1,0]
	s_waitcnt lgkmcnt(0)
	v_lshlrev_b32_e32 v6, 16, v2
	v_and_b32_e32 v7, 0xffff0000, v2
	v_pk_mul_f32 v[4:5], v[4:5], v[6:7]
	v_lshlrev_b32_e32 v6, 16, v3
	v_cvt_pk_bf16_f32 v2, v4, v5
	v_pk_mul_f32 v[4:5], v[50:51], v[0:1] op_sel_hi:[1,0]
	v_and_b32_e32 v7, 0xffff0000, v3
	v_pk_mul_f32 v[4:5], v[4:5], v[6:7]
	s_nop 0
	v_cvt_pk_bf16_f32 v3, v4, v5
	ds_write_b64 v10, v[2:3]
	v_xad_u32 v10, v9, s69, v8
	ds_read_b64 v[2:3], v10
	v_pk_mul_f32 v[4:5], v[52:53], v[0:1] op_sel_hi:[1,0]
	s_waitcnt lgkmcnt(0)
	v_lshlrev_b32_e32 v6, 16, v2
	v_and_b32_e32 v7, 0xffff0000, v2
	v_pk_mul_f32 v[4:5], v[4:5], v[6:7]
	v_lshlrev_b32_e32 v6, 16, v3
	v_cvt_pk_bf16_f32 v2, v4, v5
	v_pk_mul_f32 v[4:5], v[54:55], v[0:1] op_sel_hi:[1,0]
	v_and_b32_e32 v7, 0xffff0000, v3
	v_pk_mul_f32 v[4:5], v[4:5], v[6:7]
	s_nop 0
	v_cvt_pk_bf16_f32 v3, v4, v5
	ds_write_b64 v10, v[2:3]
	v_xad_u32 v10, v9, s70, v8
	ds_read_b64 v[2:3], v10
	v_pk_mul_f32 v[4:5], v[56:57], v[0:1] op_sel_hi:[1,0]
	s_waitcnt lgkmcnt(0)
	v_lshlrev_b32_e32 v6, 16, v2
	v_and_b32_e32 v7, 0xffff0000, v2
	v_pk_mul_f32 v[4:5], v[4:5], v[6:7]
	v_lshlrev_b32_e32 v6, 16, v3
	v_cvt_pk_bf16_f32 v2, v4, v5
	v_pk_mul_f32 v[4:5], v[58:59], v[0:1] op_sel_hi:[1,0]
	v_and_b32_e32 v7, 0xffff0000, v3
	v_pk_mul_f32 v[4:5], v[4:5], v[6:7]
	s_nop 0
	v_cvt_pk_bf16_f32 v3, v4, v5
	ds_write_b64 v10, v[2:3]
	v_xad_u32 v10, v9, s71, v8
	ds_read_b64 v[2:3], v10
	v_pk_mul_f32 v[4:5], v[60:61], v[0:1] op_sel_hi:[1,0]
	s_waitcnt lgkmcnt(0)
	v_lshlrev_b32_e32 v6, 16, v2
	v_and_b32_e32 v7, 0xffff0000, v2
	v_pk_mul_f32 v[4:5], v[4:5], v[6:7]
	v_lshlrev_b32_e32 v6, 16, v3
	v_cvt_pk_bf16_f32 v2, v4, v5
	v_pk_mul_f32 v[4:5], v[62:63], v[0:1] op_sel_hi:[1,0]
	v_and_b32_e32 v7, 0xffff0000, v3
	v_pk_mul_f32 v[4:5], v[4:5], v[6:7]
	s_nop 0
	v_cvt_pk_bf16_f32 v3, v4, v5
	ds_write_b64 v10, v[2:3]
	v_xad_u32 v10, v9, s72, v8
	ds_read_b64 v[2:3], v10
	v_pk_mul_f32 v[4:5], v[32:33], v[0:1] op_sel_hi:[1,0]
	s_waitcnt lgkmcnt(0)
	v_lshlrev_b32_e32 v6, 16, v2
	v_and_b32_e32 v7, 0xffff0000, v2
	v_pk_mul_f32 v[4:5], v[4:5], v[6:7]
	v_lshlrev_b32_e32 v6, 16, v3
	v_cvt_pk_bf16_f32 v2, v4, v5
	v_pk_mul_f32 v[4:5], v[34:35], v[0:1] op_sel_hi:[1,0]
	v_and_b32_e32 v7, 0xffff0000, v3
	v_pk_mul_f32 v[4:5], v[4:5], v[6:7]
	s_nop 0
	v_cvt_pk_bf16_f32 v3, v4, v5
	ds_write_b64 v10, v[2:3]
	v_xad_u32 v10, v9, s73, v8
	ds_read_b64 v[2:3], v10
	v_pk_mul_f32 v[4:5], v[36:37], v[0:1] op_sel_hi:[1,0]
	s_waitcnt lgkmcnt(0)
	v_lshlrev_b32_e32 v6, 16, v2
	v_and_b32_e32 v7, 0xffff0000, v2
	v_pk_mul_f32 v[4:5], v[4:5], v[6:7]
	v_lshlrev_b32_e32 v6, 16, v3
	v_cvt_pk_bf16_f32 v2, v4, v5
	v_pk_mul_f32 v[4:5], v[38:39], v[0:1] op_sel_hi:[1,0]
	v_and_b32_e32 v7, 0xffff0000, v3
	v_pk_mul_f32 v[4:5], v[4:5], v[6:7]
	s_nop 0
	v_cvt_pk_bf16_f32 v3, v4, v5
	ds_write_b64 v10, v[2:3]
	v_xad_u32 v10, v9, s79, v8
	ds_read_b64 v[2:3], v10
	v_pk_mul_f32 v[4:5], v[40:41], v[0:1] op_sel_hi:[1,0]
	s_waitcnt lgkmcnt(0)
	v_lshlrev_b32_e32 v6, 16, v2
	v_and_b32_e32 v7, 0xffff0000, v2
	v_pk_mul_f32 v[4:5], v[4:5], v[6:7]
	v_lshlrev_b32_e32 v6, 16, v3
	v_cvt_pk_bf16_f32 v2, v4, v5
	v_pk_mul_f32 v[4:5], v[42:43], v[0:1] op_sel_hi:[1,0]
	v_and_b32_e32 v7, 0xffff0000, v3
	v_pk_mul_f32 v[4:5], v[4:5], v[6:7]
	s_nop 0
	v_cvt_pk_bf16_f32 v3, v4, v5
	ds_write_b64 v10, v[2:3]
	v_xad_u32 v10, v9, s80, v8
	ds_read_b64 v[2:3], v10
	v_pk_mul_f32 v[4:5], v[44:45], v[0:1] op_sel_hi:[1,0]
	s_waitcnt lgkmcnt(0)
	v_lshlrev_b32_e32 v6, 16, v2
	v_and_b32_e32 v7, 0xffff0000, v2
	v_pk_mul_f32 v[4:5], v[4:5], v[6:7]
	v_lshlrev_b32_e32 v6, 16, v3
	v_cvt_pk_bf16_f32 v2, v4, v5
	v_pk_mul_f32 v[4:5], v[46:47], v[0:1] op_sel_hi:[1,0]
	v_and_b32_e32 v7, 0xffff0000, v3
	v_pk_mul_f32 v[4:5], v[4:5], v[6:7]
	s_nop 0
	v_cvt_pk_bf16_f32 v3, v4, v5
	ds_write_b64 v10, v[2:3]
	v_xad_u32 v10, v9, s81, v8
	ds_read_b64 v[2:3], v10
	v_pk_mul_f32 v[4:5], v[16:17], v[0:1] op_sel_hi:[1,0]
	s_waitcnt lgkmcnt(0)
	v_lshlrev_b32_e32 v6, 16, v2
	v_and_b32_e32 v7, 0xffff0000, v2
	v_pk_mul_f32 v[4:5], v[4:5], v[6:7]
	v_lshlrev_b32_e32 v6, 16, v3
	v_cvt_pk_bf16_f32 v2, v4, v5
	v_pk_mul_f32 v[4:5], v[18:19], v[0:1] op_sel_hi:[1,0]
	v_and_b32_e32 v7, 0xffff0000, v3
	v_pk_mul_f32 v[4:5], v[4:5], v[6:7]
	s_nop 0
	v_cvt_pk_bf16_f32 v3, v4, v5
	ds_write_b64 v10, v[2:3]
	v_xad_u32 v10, v9, s82, v8
	ds_read_b64 v[2:3], v10
	v_pk_mul_f32 v[4:5], v[20:21], v[0:1] op_sel_hi:[1,0]
	s_waitcnt lgkmcnt(0)
	v_lshlrev_b32_e32 v6, 16, v2
	v_and_b32_e32 v7, 0xffff0000, v2
	v_pk_mul_f32 v[4:5], v[4:5], v[6:7]
	v_lshlrev_b32_e32 v6, 16, v3
	v_cvt_pk_bf16_f32 v2, v4, v5
	v_pk_mul_f32 v[4:5], v[22:23], v[0:1] op_sel_hi:[1,0]
	v_and_b32_e32 v7, 0xffff0000, v3
	v_pk_mul_f32 v[4:5], v[4:5], v[6:7]
	s_nop 0
	v_cvt_pk_bf16_f32 v3, v4, v5
	ds_write_b64 v10, v[2:3]
	v_xad_u32 v10, v9, s83, v8
	ds_read_b64 v[2:3], v10
	v_pk_mul_f32 v[4:5], v[24:25], v[0:1] op_sel_hi:[1,0]
	v_xad_u32 v8, v9, s84, v8
	s_waitcnt lgkmcnt(0)
	v_lshlrev_b32_e32 v6, 16, v2
	v_and_b32_e32 v7, 0xffff0000, v2
	v_pk_mul_f32 v[4:5], v[4:5], v[6:7]
	v_lshlrev_b32_e32 v6, 16, v3
	v_cvt_pk_bf16_f32 v2, v4, v5
	v_pk_mul_f32 v[4:5], v[26:27], v[0:1] op_sel_hi:[1,0]
	v_and_b32_e32 v7, 0xffff0000, v3
	v_pk_mul_f32 v[4:5], v[4:5], v[6:7]
	s_nop 0
	v_cvt_pk_bf16_f32 v3, v4, v5
	ds_write_b64 v10, v[2:3]
	ds_read_b64 v[2:3], v8
	v_pk_mul_f32 v[4:5], v[28:29], v[0:1] op_sel_hi:[1,0]
	s_waitcnt lgkmcnt(0)
	v_lshlrev_b32_e32 v6, 16, v2
	v_and_b32_e32 v7, 0xffff0000, v2
	v_pk_mul_f32 v[4:5], v[4:5], v[6:7]
	v_lshlrev_b32_e32 v6, 16, v3
	v_cvt_pk_bf16_f32 v2, v4, v5
	v_pk_mul_f32 v[4:5], v[30:31], v[0:1] op_sel_hi:[1,0]
	v_and_b32_e32 v7, 0xffff0000, v3
	v_pk_mul_f32 v[4:5], v[4:5], v[6:7]
	v_lshlrev_b32_e32 v0, 4, v174
	v_cvt_pk_bf16_f32 v3, v4, v5
	v_and_b32_e32 v0, 0xf0, v0
	ds_write_b64 v8, v[2:3]
	v_add_u32_e32 v18, s61, v0
	s_waitcnt lgkmcnt(0)
	v_lshl_add_u32 v6, v170, 8, v18
	ds_read_b128 v[2:5], v6
	v_mul_u32_u24_e32 v0, 0x1400, v170
	v_lshl_add_u64 v[14:15], s[0:1], 0, v[0:1]
	v_lshl_add_u64 v[10:11], v[14:15], 0, v[144:145]
	v_lshl_add_u32 v0, v147, 8, v18
	v_mov_b32_e32 v147, v1
	s_waitcnt lgkmcnt(0)
	global_store_dwordx4 v[10:11], v[2:5], off
	v_lshl_add_u64 v[10:11], v[14:15], 0, v[146:147]
	ds_read_b128 v[6:9], v6 offset:4096
	ds_read_b128 v[2:5], v0
	v_add_co_u32_e32 v16, vcc, s86, v10
	v_lshl_add_u32 v0, v149, 8, v18
	s_nop 0
	v_addc_co_u32_e32 v17, vcc, 0, v11, vcc
	ds_read_b128 v[10:13], v0
	v_lshl_add_u64 v[14:15], v[14:15], 0, s[48:49]
	v_mov_b32_e32 v149, v1
	s_waitcnt lgkmcnt(0)
	global_store_dwordx4 v[16:17], v[2:5], off
	v_lshl_add_u32 v0, v153, 8, v18
	v_mov_b32_e32 v153, v1
	v_lshl_add_u64 v[2:3], v[14:15], 0, v[148:149]
	global_store_dwordx4 v[2:3], v[10:13], off
	ds_read_b128 v[2:5], v0
	v_lshl_add_u32 v0, v151, 8, v18
	v_lshl_add_u64 v[10:11], v[14:15], 0, v[152:153]
	v_add_co_u32_e32 v14, vcc, s86, v10
	v_mov_b32_e32 v151, v1
	s_nop 0
	v_addc_co_u32_e32 v15, vcc, 0, v11, vcc
	ds_read_b128 v[10:13], v0
	v_mad_u32_u24 v0, v170, s85, v196
	s_waitcnt lgkmcnt(0)
	global_store_dwordx4 v[14:15], v[2:5], off
	s_nop 1
	v_lshl_add_u64 v[2:3], s[0:1], 0, v[0:1]
	v_lshl_add_u64 v[2:3], v[2:3], 0, v[144:145]
	v_mad_u32_u24 v0, v170, s85, v197
	global_store_dwordx4 v[2:3], v[6:9], off
	v_lshl_add_u64 v[2:3], s[0:1], 0, v[0:1]
	v_lshl_add_u64 v[2:3], v[2:3], 0, v[150:151]
	v_lshl_add_u32 v0, v155, 8, v18
	global_store_dwordx4 v[2:3], v[10:13], off
	ds_read_b128 v[2:5], v0
	v_mad_u32_u24 v0, v170, s85, v198
	v_lshl_add_u64 v[6:7], s[0:1], 0, v[0:1]
	v_mov_b32_e32 v155, v1
	v_lshl_add_u32 v0, v157, 8, v18
	v_lshl_add_u64 v[10:11], v[6:7], 0, v[154:155]
	ds_read_b128 v[6:9], v0
	v_mad_u32_u24 v0, v170, s85, v199
	s_waitcnt lgkmcnt(0)
	global_store_dwordx4 v[10:11], v[2:5], off
	v_mov_b32_e32 v157, v1
	s_nop 0
	v_lshl_add_u64 v[2:3], s[0:1], 0, v[0:1]
	v_lshl_add_u64 v[2:3], v[2:3], 0, v[156:157]
	global_store_dwordx4 v[2:3], v[6:9], off
	s_waitcnt lgkmcnt(0)

.LBB0_457:
	s_waitcnt vmcnt(0)
	s_mov_b64 s[100:101], exec
	s_mov_b64 exec, s[4:5]
	ds_write_b32 v173, v171 offset:4
	s_mov_b64 exec, s[100:101]
	s_waitcnt lgkmcnt(0)
	s_add_i32 s58, s59, 1
	s_cmp_ge_u32 s58, s56
	s_barrier
	s_cbranch_scc1 .Lpf_in_2
	s_cmp_lt_u32 s59, 3
	s_cselect_b32 s0, s20, 0xffffff00
	s_add_i32 s0, s0, s57
	s_add_i32 s0, s0, 64
	s_ashr_i32 s1, s0, 31
	s_add_i32 s2, s55, 0x4000
	s_and_b32 s52, s2, 0x4000
	v_lshl_add_u64 v[2:3], s[0:1], 0, v[158:159]
	v_mad_u64_u32 v[4:5], s[2:3], v2, s62, v[162:163]
	s_add_i32 s52, s52, 0
	v_mad_i32_i24 v5, v3, s62, v5
	s_add_i32 s53, s52, s91
	v_lshl_add_u64 v[4:5], v[4:5], 0, s[24:25]
	s_mov_b32 m0, s53
	s_nop 0
	global_load_lds_dwordx4 v[4:5], off
	v_mad_u64_u32 v[4:5], s[2:3], v2, s62, v[164:165]
	v_mad_i32_i24 v5, v3, s62, v5
	s_add_i32 m0, s53, 0x8000
	v_lshl_add_u64 v[2:3], s[0:1], 0, v[160:161]
	global_load_lds_dwordx4 v[4:5], off
	v_mad_u64_u32 v[4:5], s[0:1], v2, s62, v[166:167]
	v_mad_i32_i24 v5, v3, s62, v5
	s_add_i32 s2, s52, s92
	v_lshl_add_u64 v[4:5], v[4:5], 0, s[24:25]
	s_mov_b32 m0, s2
	s_nop 0
	global_load_lds_dwordx4 v[4:5], off
	v_mad_u64_u32 v[4:5], s[0:1], v2, s62, v[168:169]
	v_mad_i32_i24 v5, v3, s62, v5
	s_add_i32 m0, s2, 0x8000
	s_nop 0
	global_load_lds_dwordx4 v[4:5], off
	s_branch .LBB0_459

.Lpf_done_2:
.LBB0_459:
	s_cmp_lt_u32 s59, 4
	s_cselect_b64 s[0:1], -1, 0
	s_cmp_gt_u32 s59, 3
	s_mov_b64 s[52:53], -1
	s_cbranch_scc0 .LBB0_462
	s_add_i32 s2, s59, -4
	s_lshr_b32 s2, s2, 2
	v_lshrrev_b32_e32 v0, s2, v178
	v_bfe_u32 v2, v178, s2, 1
	v_and_b32_e32 v0, 1, v0
	v_cmp_ne_u32_e32 vcc, 0, v2
	s_cmp_eq_u64 vcc, 0
	v_cmp_eq_u32_e32 vcc, 1, v0
	s_cselect_b64 s[2:3], -1, 0
	s_nop 0
	v_cndmask_b32_e64 v80, v195, 0, vcc
	s_cbranch_execz .LBB0_463

.LBB0_472:
	v_lshl_add_u64 v[86:87], v[176:177], 0, s[0:1]
	s_mov_b32 s2, 0x5000000
	v_add_co_u32_e32 v82, vcc, s2, v86
	s_mov_b32 s2, 0x5001000
	s_nop 0
	v_addc_co_u32_e32 v83, vcc, 0, v87, vcc
	v_lshl_add_u64 v[66:67], v[184:185], 0, s[0:1]
	v_lshl_add_u64 v[70:71], v[182:183], 0, s[0:1]
	v_lshl_add_u64 v[74:75], v[180:181], 0, s[0:1]
	v_lshl_add_u64 v[78:79], v[178:179], 0, s[0:1]
	v_add_co_u32_e32 v86, vcc, s2, v86
	global_load_dwordx4 v[66:69], v[66:67], off
	s_nop 0
	global_load_dwordx4 v[70:73], v[70:71], off
	s_nop 0
	global_load_dwordx4 v[74:77], v[74:75], off
	s_nop 0
	global_load_dwordx4 v[78:81], v[78:79], off
	v_addc_co_u32_e32 v87, vcc, 0, v87, vcc
	global_load_dwordx4 v[82:85], v[82:83], off offset:2048
	v_add_u32_e32 v0, 0x9000, v210
	global_load_dwordx4 v[86:89], v[86:87], off offset:2048
	s_waitcnt vmcnt(0) lgkmcnt(0)
	s_mov_b64 s[100:101], exec
	s_mov_b64 exec, s[4:5]
	ds_write_b32 v173, v171 offset:4
	s_mov_b64 exec, s[100:101]
	s_waitcnt lgkmcnt(0)
	s_barrier
	ds_write_b128 v206, v[66:69]
	ds_write_b128 v207, v[70:73]
	ds_write_b128 v208, v[74:77]
	ds_write_b128 v209, v[78:81]
	v_and_b32_e32 v66, 0xffff, v82
	v_lshrrev_b32_e32 v67, 16, v82
	v_and_b32_e32 v68, 0xffff, v83
	v_lshrrev_b32_e32 v69, 16, v83
	v_and_b32_e32 v70, 0xffff, v84
	v_lshrrev_b32_e32 v71, 16, v84
	v_and_b32_e32 v72, 0xffff, v85
	v_lshrrev_b32_e32 v73, 16, v85
	v_lshl_or_b32 v66, v86, 16, v66
	v_and_or_b32 v67, v86, s68, v67
	v_lshl_or_b32 v68, v87, 16, v68
	v_and_or_b32 v69, v87, s68, v69
	v_lshl_or_b32 v70, v88, 16, v70
	v_and_or_b32 v71, v88, s68, v71
	v_lshl_or_b32 v72, v89, 16, v72
	v_and_or_b32 v73, v89, s68, v73
	ds_write2_b32 v0, v66, v67 offset1:36
	ds_write2_b32 v0, v68, v69 offset0:72 offset1:108
	ds_write2_b32 v0, v70, v71 offset0:144 offset1:180
	ds_write2_b32 v0, v72, v73 offset0:216 offset1:252
	s_waitcnt lgkmcnt(0)
	s_barrier
	ds_read_b128 v[66:69], v211
	ds_read_b128 v[226:229], v211 offset:32
	s_waitcnt lgkmcnt(1)
	v_mfma_f32_32x32x16_bf16 v[66:81], v[66:69], v[98:101], 0
	ds_read_b128 v[82:85], v211 offset:16896
	ds_read_b128 v[230:233], v211 offset:16928
	v_mov_b32_e32 v0, v225
	s_waitcnt lgkmcnt(1)
	v_mfma_f32_32x32x16_bf16 v[82:97], v[82:85], v[98:101], 0
	v_mfma_f32_32x32x16_bf16 v[66:81], v[226:229], v[102:105], v[66:81]
	s_waitcnt lgkmcnt(0)
	v_mfma_f32_32x32x16_bf16 v[82:97], v[230:233], v[102:105], v[82:97]
	ds_read_b128 v[226:229], v211 offset:64
	ds_read_b128 v[230:233], v211 offset:96
	s_waitcnt lgkmcnt(1)
	v_mfma_f32_32x32x16_bf16 v[66:81], v[226:229], v[106:109], v[66:81]
	ds_read_b128 v[226:229], v211 offset:16960
	ds_read_b128 v[234:237], v211 offset:16992
	s_waitcnt lgkmcnt(2)
	v_mfma_f32_32x32x16_bf16 v[66:81], v[230:233], v[110:113], v[66:81]
	s_waitcnt lgkmcnt(1)
	v_mfma_f32_32x32x16_bf16 v[82:97], v[226:229], v[106:109], v[82:97]
	ds_read_b128 v[226:229], v211 offset:128
	ds_read_b128 v[230:233], v211 offset:160
	s_waitcnt lgkmcnt(1)
	v_mfma_f32_32x32x16_bf16 v[66:81], v[226:229], v[114:117], v[66:81]
	v_mfma_f32_32x32x16_bf16 v[82:97], v[234:237], v[110:113], v[82:97]
	ds_read_b128 v[226:229], v211 offset:17024
	ds_read_b128 v[234:237], v211 offset:17056
	s_waitcnt lgkmcnt(2)
	v_mfma_f32_32x32x16_bf16 v[66:81], v[230:233], v[118:121], v[66:81]
	s_waitcnt lgkmcnt(1)
	v_mfma_f32_32x32x16_bf16 v[82:97], v[226:229], v[114:117], v[82:97]
	ds_read_b128 v[226:229], v211 offset:192
	ds_read_b128 v[230:233], v211 offset:224
	s_waitcnt lgkmcnt(1)
	v_mfma_f32_32x32x16_bf16 v[66:81], v[226:229], v[122:125], v[66:81]
	v_mfma_f32_32x32x16_bf16 v[82:97], v[234:237], v[118:121], v[82:97]
	ds_read_b128 v[226:229], v211 offset:17088
	ds_read_b128 v[234:237], v211 offset:17120
	s_waitcnt lgkmcnt(2)
	v_mfma_f32_32x32x16_bf16 v[66:81], v[230:233], v[126:129], v[66:81]
	s_waitcnt lgkmcnt(1)
	v_mfma_f32_32x32x16_bf16 v[82:97], v[226:229], v[122:125], v[82:97]
	ds_read_b128 v[226:229], v211 offset:256
	ds_read_b128 v[230:233], v211 offset:288
	s_waitcnt lgkmcnt(1)
	v_mfma_f32_32x32x16_bf16 v[66:81], v[226:229], v[130:133], v[66:81]
	v_mfma_f32_32x32x16_bf16 v[82:97], v[234:237], v[126:129], v[82:97]
	ds_read_b128 v[226:229], v211 offset:17152
	ds_read_b128 v[234:237], v211 offset:17184
	s_waitcnt lgkmcnt(2)
	v_mfma_f32_32x32x16_bf16 v[66:81], v[230:233], v[134:137], v[66:81]
	s_waitcnt lgkmcnt(1)
	v_mfma_f32_32x32x16_bf16 v[82:97], v[226:229], v[130:133], v[82:97]
	ds_read_b128 v[226:229], v211 offset:320
	ds_read_b128 v[230:233], v211 offset:352
	s_waitcnt lgkmcnt(1)
	v_mfma_f32_32x32x16_bf16 v[66:81], v[226:229], v[138:141], v[66:81]
	s_waitcnt lgkmcnt(0)
	v_mfma_f32_32x32x16_bf16 v[66:81], v[230:233], v[142:145], v[66:81]
	ds_read_b128 v[226:229], v211 offset:384
	ds_read_b128 v[230:233], v211 offset:416
	s_waitcnt lgkmcnt(1)
	v_mfma_f32_32x32x16_bf16 v[66:81], v[226:229], v[146:149], v[66:81]
	s_waitcnt lgkmcnt(0)
	v_mfma_f32_32x32x16_bf16 v[66:81], v[230:233], v[150:153], v[66:81]
	ds_read_b128 v[226:229], v211 offset:448
	ds_read_b128 v[230:233], v211 offset:480
	s_waitcnt lgkmcnt(1)
	v_mfma_f32_32x32x16_bf16 v[66:81], v[226:229], v[154:157], v[66:81]
	v_mfma_f32_32x32x16_bf16 v[82:97], v[234:237], v[134:137], v[82:97]
	s_waitcnt lgkmcnt(0)
	v_mfma_f32_32x32x16_bf16 v[66:81], v[230:233], v[158:161], v[66:81]
	ds_read_b128 v[226:229], v211 offset:17216
	ds_read_b128 v[230:233], v211 offset:17248
	s_waitcnt lgkmcnt(1)
	v_mfma_f32_32x32x16_bf16 v[82:97], v[226:229], v[138:141], v[82:97]
	s_nop 7
	v_max_f32_e32 v186, v67, v67
	v_max_f32_e32 v225, v66, v66
	v_max_f32_e32 v186, v225, v186
	v_max3_f32 v186, v186, v68, v69
	v_max3_f32 v186, v186, v70, v71
	v_max3_f32 v186, v186, v72, v73
	v_max3_f32 v186, v186, v74, v75
	s_waitcnt lgkmcnt(0)
	v_mfma_f32_32x32x16_bf16 v[82:97], v[230:233], v[142:145], v[82:97]
	ds_read_b128 v[226:229], v211 offset:17280
	ds_read_b128 v[230:233], v211 offset:17312
	v_max3_f32 v186, v186, v76, v77
	v_max3_f32 v186, v186, v78, v79
	v_max3_f32 v186, v186, v80, v81
	s_waitcnt lgkmcnt(1)
	v_mfma_f32_32x32x16_bf16 v[82:97], v[226:229], v[146:149], v[82:97]
	ds_read_b128 v[226:229], v211 offset:17344
	s_waitcnt lgkmcnt(1)
	v_mfma_f32_32x32x16_bf16 v[82:97], v[230:233], v[150:153], v[82:97]
	ds_read_b128 v[230:233], v211 offset:17376
	s_waitcnt lgkmcnt(1)
	v_mfma_f32_32x32x16_bf16 v[82:97], v[226:229], v[154:157], v[82:97]
	s_waitcnt lgkmcnt(0)
	v_mfma_f32_32x32x16_bf16 v[82:97], v[230:233], v[158:161], v[82:97]
	s_nop 11
	v_max3_f32 v186, v186, v82, v83
	v_max3_f32 v186, v186, v84, v85
	v_max3_f32 v186, v186, v86, v87
	v_max3_f32 v186, v186, v88, v89
	v_max3_f32 v186, v186, v90, v91
	v_max3_f32 v186, v186, v92, v93
	v_max3_f32 v186, v186, v94, v95
	v_max3_f32 v186, v186, v96, v97
	v_mov_b32_e32 v225, v186
	s_nop 1
	v_permlane32_swap_b32_e32 v186, v225
	v_max3_f32 v225, v0, v186, v225
	v_sub_f32_e32 v0, v0, v225
	v_exp_f32_e32 v186, v0
	s_nop 0
	v_cmp_neq_f32_e32 vcc, 1.0, v186
	s_cbranch_vccz .LBB0_474
	v_pk_mul_f32 v[64:65], v[64:65], v[186:187] op_sel_hi:[1,0]
	v_pk_mul_f32 v[62:63], v[62:63], v[186:187] op_sel_hi:[1,0]
	v_pk_mul_f32 v[60:61], v[60:61], v[186:187] op_sel_hi:[1,0]
	v_pk_mul_f32 v[58:59], v[58:59], v[186:187] op_sel_hi:[1,0]
	v_pk_mul_f32 v[56:57], v[56:57], v[186:187] op_sel_hi:[1,0]
	v_pk_mul_f32 v[54:55], v[54:55], v[186:187] op_sel_hi:[1,0]
	v_pk_mul_f32 v[52:53], v[52:53], v[186:187] op_sel_hi:[1,0]
	v_pk_mul_f32 v[50:51], v[50:51], v[186:187] op_sel_hi:[1,0]
	v_pk_mul_f32 v[48:49], v[48:49], v[186:187] op_sel_hi:[1,0]
	v_pk_mul_f32 v[46:47], v[46:47], v[186:187] op_sel_hi:[1,0]
	v_pk_mul_f32 v[44:45], v[44:45], v[186:187] op_sel_hi:[1,0]
	v_pk_mul_f32 v[42:43], v[42:43], v[186:187] op_sel_hi:[1,0]
	v_pk_mul_f32 v[40:41], v[40:41], v[186:187] op_sel_hi:[1,0]
	v_pk_mul_f32 v[38:39], v[38:39], v[186:187] op_sel_hi:[1,0]
	v_pk_mul_f32 v[36:37], v[36:37], v[186:187] op_sel_hi:[1,0]
	v_pk_mul_f32 v[34:35], v[34:35], v[186:187] op_sel_hi:[1,0]
	v_pk_mul_f32 v[32:33], v[32:33], v[186:187] op_sel_hi:[1,0]
	v_pk_mul_f32 v[30:31], v[30:31], v[186:187] op_sel_hi:[1,0]
	v_pk_mul_f32 v[28:29], v[28:29], v[186:187] op_sel_hi:[1,0]
	v_pk_mul_f32 v[26:27], v[26:27], v[186:187] op_sel_hi:[1,0]
	v_pk_mul_f32 v[24:25], v[24:25], v[186:187] op_sel_hi:[1,0]
	v_pk_mul_f32 v[22:23], v[22:23], v[186:187] op_sel_hi:[1,0]
	v_pk_mul_f32 v[20:21], v[20:21], v[186:187] op_sel_hi:[1,0]
	v_pk_mul_f32 v[18:19], v[18:19], v[186:187] op_sel_hi:[1,0]
	v_pk_mul_f32 v[16:17], v[16:17], v[186:187] op_sel_hi:[1,0]
	v_pk_mul_f32 v[14:15], v[14:15], v[186:187] op_sel_hi:[1,0]
	v_pk_mul_f32 v[12:13], v[12:13], v[186:187] op_sel_hi:[1,0]
	v_pk_mul_f32 v[10:11], v[10:11], v[186:187] op_sel_hi:[1,0]
	v_pk_mul_f32 v[8:9], v[8:9], v[186:187] op_sel_hi:[1,0]
	v_pk_mul_f32 v[6:7], v[6:7], v[186:187] op_sel_hi:[1,0]
	v_pk_mul_f32 v[4:5], v[4:5], v[186:187] op_sel_hi:[1,0]
	v_pk_mul_f32 v[2:3], v[2:3], v[186:187] op_sel_hi:[1,0]

.Lpf_done_4:
	v_mov_b32_e32 v66, v0
	s_nop 1
	v_permlane32_swap_b32_e32 v0, v66
	v_add_f32_e32 v0, v0, v66
	v_div_scale_f32 v66, s[0:1], v0, v0, 1.0
	v_rcp_f32_e32 v68, v66
	s_waitcnt vmcnt(3)
	s_mulk_i32 s55, 0x1400
	s_mul_hi_u32 s0, s54, 0x1400
	v_fma_f32 v67, -v66, v68, 1.0
	v_fmac_f32_e32 v68, v67, v68
	v_div_scale_f32 v67, vcc, 1.0, v0, 1.0
	v_mul_f32_e32 v69, v67, v68
	v_fma_f32 v70, -v66, v69, v67
	v_fmac_f32_e32 v69, v70, v68
	v_fma_f32 v70, -v66, v69, v67
	v_lshlrev_b32_e32 v66, 8, v204
	v_add3_u32 v71, s53, v66, v205
	v_lshlrev_b32_e32 v66, 4, v203
	v_and_b32_e32 v72, 0xf0, v66
	v_add_u32_e32 v73, v71, v72
	ds_read_b64 v[66:67], v73
	v_div_fmas_f32 v68, v70, v68, v69
	v_div_fixup_f32 v0, v68, v0, 1.0
	v_pk_mul_f32 v[50:51], v[50:51], v[0:1] op_sel_hi:[1,0]
	v_pk_mul_f32 v[52:53], v[52:53], v[0:1] op_sel_hi:[1,0]
	s_waitcnt lgkmcnt(0)
	v_lshlrev_b32_e32 v68, 16, v66
	v_and_b32_e32 v69, 0xffff0000, v66
	v_lshlrev_b32_e32 v66, 16, v67
	v_and_b32_e32 v67, 0xffff0000, v67
	v_pk_mul_f32 v[50:51], v[50:51], v[68:69]
	v_pk_mul_f32 v[52:53], v[52:53], v[66:67]
	v_cvt_pk_bf16_f32 v50, v50, v51
	v_cvt_pk_bf16_f32 v51, v52, v53
	ds_write_b64 v73, v[50:51]
	v_xad_u32 v66, v72, 16, v71
	ds_read_b64 v[50:51], v66
	v_pk_mul_f32 v[52:53], v[54:55], v[0:1] op_sel_hi:[1,0]
	v_pk_mul_f32 v[34:35], v[34:35], v[0:1] op_sel_hi:[1,0]
	v_pk_mul_f32 v[36:37], v[36:37], v[0:1] op_sel_hi:[1,0]
	v_pk_mul_f32 v[18:19], v[18:19], v[0:1] op_sel_hi:[1,0]
	s_waitcnt lgkmcnt(0)
	v_lshlrev_b32_e32 v54, 16, v50
	v_and_b32_e32 v55, 0xffff0000, v50
	v_pk_mul_f32 v[52:53], v[52:53], v[54:55]
	v_lshlrev_b32_e32 v54, 16, v51
	v_cvt_pk_bf16_f32 v50, v52, v53
	v_pk_mul_f32 v[52:53], v[56:57], v[0:1] op_sel_hi:[1,0]
	v_and_b32_e32 v55, 0xffff0000, v51
	v_pk_mul_f32 v[52:53], v[52:53], v[54:55]
	v_xad_u32 v56, v72, 32, v71
	v_cvt_pk_bf16_f32 v51, v52, v53
	ds_write_b64 v66, v[50:51]
	ds_read_b64 v[50:51], v56
	v_pk_mul_f32 v[52:53], v[58:59], v[0:1] op_sel_hi:[1,0]
	v_pk_mul_f32 v[20:21], v[20:21], v[0:1] op_sel_hi:[1,0]
	v_pk_mul_f32 v[2:3], v[2:3], v[0:1] op_sel_hi:[1,0]
	v_pk_mul_f32 v[4:5], v[4:5], v[0:1] op_sel_hi:[1,0]
	s_waitcnt lgkmcnt(0)
	v_lshlrev_b32_e32 v54, 16, v50
	v_and_b32_e32 v55, 0xffff0000, v50
	v_pk_mul_f32 v[52:53], v[52:53], v[54:55]
	v_lshlrev_b32_e32 v54, 16, v51
	v_cvt_pk_bf16_f32 v50, v52, v53
	v_pk_mul_f32 v[52:53], v[60:61], v[0:1] op_sel_hi:[1,0]
	v_and_b32_e32 v55, 0xffff0000, v51
	v_pk_mul_f32 v[52:53], v[52:53], v[54:55]
	s_add_i32 s0, s0, s55
	v_cvt_pk_bf16_f32 v51, v52, v53
	ds_write_b64 v56, v[50:51]
	v_xad_u32 v56, v72, 48, v71
	ds_read_b64 v[50:51], v56
	v_pk_mul_f32 v[52:53], v[62:63], v[0:1] op_sel_hi:[1,0]
	s_mulk_i32 s54, 0x1400
	s_add_u32 s1, s30, s54
	s_addc_u32 s0, s31, s0
	s_waitcnt lgkmcnt(0)
	v_lshlrev_b32_e32 v54, 16, v50
	v_and_b32_e32 v55, 0xffff0000, v50
	v_pk_mul_f32 v[52:53], v[52:53], v[54:55]
	v_lshlrev_b32_e32 v54, 16, v51
	v_cvt_pk_bf16_f32 v50, v52, v53
	v_pk_mul_f32 v[52:53], v[64:65], v[0:1] op_sel_hi:[1,0]
	v_and_b32_e32 v55, 0xffff0000, v51
	v_pk_mul_f32 v[52:53], v[52:53], v[54:55]
	v_xad_u32 v54, v72, 64, v71
	v_cvt_pk_bf16_f32 v51, v52, v53
	ds_write_b64 v56, v[50:51]
	ds_read_b64 v[50:51], v54
	s_lshl_b32 s2, s52, 1
	s_add_u32 s1, s1, s2
	s_addc_u32 s2, s0, 0
	s_lshl_b32 s0, s20, 1
	s_waitcnt lgkmcnt(0)
	v_lshlrev_b32_e32 v52, 16, v50
	v_and_b32_e32 v53, 0xffff0000, v50
	v_lshlrev_b32_e32 v50, 16, v51
	v_and_b32_e32 v51, 0xffff0000, v51
	v_pk_mul_f32 v[34:35], v[34:35], v[52:53]
	v_pk_mul_f32 v[36:37], v[36:37], v[50:51]
	v_cvt_pk_bf16_f32 v34, v34, v35
	v_cvt_pk_bf16_f32 v35, v36, v37
	ds_write_b64 v54, v[34:35]
	v_xad_u32 v50, v72, s69, v71
	ds_read_b64 v[34:35], v50
	v_pk_mul_f32 v[36:37], v[38:39], v[0:1] op_sel_hi:[1,0]
	s_add_u32 s0, s1, s0
	s_addc_u32 s1, s2, 0
	s_mov_b64 s[2:3], -1
	s_waitcnt lgkmcnt(0)
	v_lshlrev_b32_e32 v38, 16, v34
	v_and_b32_e32 v39, 0xffff0000, v34
	v_pk_mul_f32 v[36:37], v[36:37], v[38:39]
	v_lshlrev_b32_e32 v38, 16, v35
	v_cvt_pk_bf16_f32 v34, v36, v37
	v_pk_mul_f32 v[36:37], v[40:41], v[0:1] op_sel_hi:[1,0]
	v_and_b32_e32 v39, 0xffff0000, v35
	v_pk_mul_f32 v[36:37], v[36:37], v[38:39]
	v_xad_u32 v40, v72, s70, v71
	v_cvt_pk_bf16_f32 v35, v36, v37
	ds_write_b64 v50, v[34:35]
	ds_read_b64 v[34:35], v40
	v_pk_mul_f32 v[36:37], v[42:43], v[0:1] op_sel_hi:[1,0]
	s_waitcnt lgkmcnt(0)
	v_lshlrev_b32_e32 v38, 16, v34
	v_and_b32_e32 v39, 0xffff0000, v34
	v_pk_mul_f32 v[36:37], v[36:37], v[38:39]
	v_lshlrev_b32_e32 v38, 16, v35
	v_cvt_pk_bf16_f32 v34, v36, v37
	v_pk_mul_f32 v[36:37], v[44:45], v[0:1] op_sel_hi:[1,0]
	v_and_b32_e32 v39, 0xffff0000, v35
	v_pk_mul_f32 v[36:37], v[36:37], v[38:39]
	s_nop 0
	v_cvt_pk_bf16_f32 v35, v36, v37
	ds_write_b64 v40, v[34:35]
	v_xad_u32 v40, v72, s71, v71
	ds_read_b64 v[34:35], v40
	v_pk_mul_f32 v[36:37], v[46:47], v[0:1] op_sel_hi:[1,0]
	s_waitcnt lgkmcnt(0)
	v_lshlrev_b32_e32 v38, 16, v34
	v_and_b32_e32 v39, 0xffff0000, v34
	v_pk_mul_f32 v[36:37], v[36:37], v[38:39]
	v_lshlrev_b32_e32 v38, 16, v35
	v_cvt_pk_bf16_f32 v34, v36, v37
	v_pk_mul_f32 v[36:37], v[48:49], v[0:1] op_sel_hi:[1,0]
	v_and_b32_e32 v39, 0xffff0000, v35
	v_pk_mul_f32 v[36:37], v[36:37], v[38:39]
	v_xad_u32 v38, v72, s72, v71
	v_cvt_pk_bf16_f32 v35, v36, v37
	ds_write_b64 v40, v[34:35]
	ds_read_b64 v[34:35], v38
	s_waitcnt lgkmcnt(0)
	v_lshlrev_b32_e32 v36, 16, v34
	v_and_b32_e32 v37, 0xffff0000, v34
	v_lshlrev_b32_e32 v34, 16, v35
	v_and_b32_e32 v35, 0xffff0000, v35
	v_pk_mul_f32 v[18:19], v[18:19], v[36:37]
	v_pk_mul_f32 v[20:21], v[20:21], v[34:35]
	v_cvt_pk_bf16_f32 v18, v18, v19
	v_cvt_pk_bf16_f32 v19, v20, v21
	ds_write_b64 v38, v[18:19]
	v_xad_u32 v34, v72, s73, v71
	ds_read_b64 v[18:19], v34
	v_pk_mul_f32 v[20:21], v[22:23], v[0:1] op_sel_hi:[1,0]
	s_waitcnt lgkmcnt(0)
	v_lshlrev_b32_e32 v22, 16, v18
	v_and_b32_e32 v23, 0xffff0000, v18
	v_pk_mul_f32 v[20:21], v[20:21], v[22:23]
	v_lshlrev_b32_e32 v22, 16, v19
	v_cvt_pk_bf16_f32 v18, v20, v21
	v_pk_mul_f32 v[20:21], v[24:25], v[0:1] op_sel_hi:[1,0]
	v_and_b32_e32 v23, 0xffff0000, v19
	v_pk_mul_f32 v[20:21], v[20:21], v[22:23]
	v_xad_u32 v24, v72, s79, v71
	v_cvt_pk_bf16_f32 v19, v20, v21
	ds_write_b64 v34, v[18:19]
	ds_read_b64 v[18:19], v24
	v_pk_mul_f32 v[20:21], v[26:27], v[0:1] op_sel_hi:[1,0]
	s_waitcnt lgkmcnt(0)
	v_lshlrev_b32_e32 v22, 16, v18
	v_and_b32_e32 v23, 0xffff0000, v18
	v_pk_mul_f32 v[20:21], v[20:21], v[22:23]
	v_lshlrev_b32_e32 v22, 16, v19
	v_cvt_pk_bf16_f32 v18, v20, v21
	v_pk_mul_f32 v[20:21], v[28:29], v[0:1] op_sel_hi:[1,0]
	v_and_b32_e32 v23, 0xffff0000, v19
	v_pk_mul_f32 v[20:21], v[20:21], v[22:23]
	s_nop 0
	v_cvt_pk_bf16_f32 v19, v20, v21
	ds_write_b64 v24, v[18:19]
	v_xad_u32 v24, v72, s80, v71
	ds_read_b64 v[18:19], v24
	v_pk_mul_f32 v[20:21], v[30:31], v[0:1] op_sel_hi:[1,0]
	s_waitcnt lgkmcnt(0)
	v_lshlrev_b32_e32 v22, 16, v18
	v_and_b32_e32 v23, 0xffff0000, v18
	v_pk_mul_f32 v[20:21], v[20:21], v[22:23]
	v_lshlrev_b32_e32 v22, 16, v19
	v_cvt_pk_bf16_f32 v18, v20, v21
	v_pk_mul_f32 v[20:21], v[32:33], v[0:1] op_sel_hi:[1,0]
	v_and_b32_e32 v23, 0xffff0000, v19
	v_pk_mul_f32 v[20:21], v[20:21], v[22:23]
	v_xad_u32 v22, v72, s81, v71
	v_cvt_pk_bf16_f32 v19, v20, v21
	ds_write_b64 v24, v[18:19]
	ds_read_b64 v[18:19], v22
	s_waitcnt lgkmcnt(0)
	v_lshlrev_b32_e32 v20, 16, v18
	v_and_b32_e32 v21, 0xffff0000, v18
	v_lshlrev_b32_e32 v18, 16, v19
	v_and_b32_e32 v19, 0xffff0000, v19
	v_pk_mul_f32 v[2:3], v[2:3], v[20:21]
	v_pk_mul_f32 v[4:5], v[4:5], v[18:19]
	v_cvt_pk_bf16_f32 v2, v2, v3
	v_cvt_pk_bf16_f32 v3, v4, v5
	ds_write_b64 v22, v[2:3]
	v_xad_u32 v18, v72, s82, v71
	ds_read_b64 v[2:3], v18
	v_pk_mul_f32 v[4:5], v[6:7], v[0:1] op_sel_hi:[1,0]
	v_add_u32_e32 v20, s53, v72
	s_waitcnt lgkmcnt(0)
	v_lshlrev_b32_e32 v6, 16, v2
	v_and_b32_e32 v7, 0xffff0000, v2
	v_pk_mul_f32 v[4:5], v[4:5], v[6:7]
	v_lshlrev_b32_e32 v6, 16, v3
	v_cvt_pk_bf16_f32 v2, v4, v5
	v_pk_mul_f32 v[4:5], v[8:9], v[0:1] op_sel_hi:[1,0]
	v_and_b32_e32 v7, 0xffff0000, v3
	v_pk_mul_f32 v[4:5], v[4:5], v[6:7]
	v_xad_u32 v8, v72, s83, v71
	v_cvt_pk_bf16_f32 v3, v4, v5
	ds_write_b64 v18, v[2:3]
	ds_read_b64 v[2:3], v8
	v_pk_mul_f32 v[4:5], v[10:11], v[0:1] op_sel_hi:[1,0]
	s_waitcnt lgkmcnt(0)
	v_lshlrev_b32_e32 v6, 16, v2
	v_and_b32_e32 v7, 0xffff0000, v2
	v_pk_mul_f32 v[4:5], v[4:5], v[6:7]
	v_lshlrev_b32_e32 v6, 16, v3
	v_cvt_pk_bf16_f32 v2, v4, v5
	v_pk_mul_f32 v[4:5], v[12:13], v[0:1] op_sel_hi:[1,0]
	v_and_b32_e32 v7, 0xffff0000, v3
	v_pk_mul_f32 v[4:5], v[4:5], v[6:7]
	s_nop 0
	v_cvt_pk_bf16_f32 v3, v4, v5
	ds_write_b64 v8, v[2:3]
	v_xad_u32 v8, v72, s84, v71
	ds_read_b64 v[2:3], v8
	v_pk_mul_f32 v[4:5], v[14:15], v[0:1] op_sel_hi:[1,0]
	s_waitcnt lgkmcnt(0)
	v_lshlrev_b32_e32 v6, 16, v2
	v_and_b32_e32 v7, 0xffff0000, v2
	v_pk_mul_f32 v[4:5], v[4:5], v[6:7]
	v_lshlrev_b32_e32 v6, 16, v3
	v_cvt_pk_bf16_f32 v2, v4, v5
	v_pk_mul_f32 v[4:5], v[16:17], v[0:1] op_sel_hi:[1,0]
	v_and_b32_e32 v7, 0xffff0000, v3
	v_pk_mul_f32 v[4:5], v[4:5], v[6:7]
	v_lshl_add_u32 v6, v169, 8, v20
	v_cvt_pk_bf16_f32 v3, v4, v5
	ds_write_b64 v8, v[2:3]
	s_waitcnt lgkmcnt(0)
	ds_read_b128 v[2:5], v6
	v_mul_u32_u24_e32 v0, 0xa00, v169
	v_lshlrev_b32_e32 v0, 1, v0
	v_lshl_add_u64 v[14:15], s[0:1], 0, v[0:1]
	v_lshlrev_b32_e32 v16, 1, v172
	v_mov_b32_e32 v17, v1
	v_lshl_add_u64 v[10:11], v[14:15], 0, v[16:17]
	s_waitcnt lgkmcnt(0)
	global_store_dwordx4 v[10:11], v[2:5], off offset:3072
	v_lshlrev_b32_e32 v10, 1, v162
	v_mov_b32_e32 v11, v1
	v_lshl_add_u32 v2, v163, 8, v20
	ds_read_b128 v[6:9], v6 offset:4096
	ds_read_b128 v[2:5], v2
	v_lshl_add_u64 v[10:11], v[14:15], 0, v[10:11]
	v_add_co_u32_e32 v18, vcc, s86, v10
	v_lshl_add_u32 v10, v165, 8, v20
	s_nop 0
	v_addc_co_u32_e32 v19, vcc, 0, v11, vcc
	ds_read_b128 v[10:13], v10
	s_waitcnt lgkmcnt(1)
	global_store_dwordx4 v[18:19], v[2:5], off offset:3072
	v_lshl_add_u64 v[14:15], v[14:15], 0, s[48:49]
	s_nop 0
	v_lshlrev_b32_e32 v2, 1, v164
	v_mov_b32_e32 v3, v1
	v_lshl_add_u64 v[2:3], v[14:15], 0, v[2:3]
	s_waitcnt lgkmcnt(0)
	global_store_dwordx4 v[2:3], v[10:13], off offset:3072
	v_lshl_add_u32 v2, v167, 8, v20
	ds_read_b128 v[2:5], v2
	v_lshlrev_b32_e32 v10, 1, v166
	v_mov_b32_e32 v11, v1
	v_lshl_add_u64 v[10:11], v[14:15], 0, v[10:11]
	v_add_co_u32_e32 v14, vcc, s86, v10
	v_lshl_add_u32 v10, v201, 8, v20
	s_nop 0
	v_addc_co_u32_e32 v15, vcc, 0, v11, vcc
	ds_read_b128 v[10:13], v10
	s_waitcnt lgkmcnt(1)
	global_store_dwordx4 v[14:15], v[2:5], off offset:3072
	s_nop 1
	v_add_u32_e32 v2, 0x14000, v0
	v_mov_b32_e32 v3, v1
	v_lshl_add_u64 v[2:3], s[0:1], 0, v[2:3]
	v_lshl_add_u64 v[2:3], v[2:3], 0, v[16:17]
	global_store_dwordx4 v[2:3], v[6:9], off offset:3072
	v_add_u32_e32 v2, 0x19000, v0
	v_mov_b32_e32 v3, v1
	v_lshl_add_u64 v[2:3], s[0:1], 0, v[2:3]
	v_lshlrev_b32_e32 v4, 1, v168
	v_mov_b32_e32 v5, v1
	v_lshl_add_u64 v[2:3], v[2:3], 0, v[4:5]
	s_waitcnt lgkmcnt(0)
	global_store_dwordx4 v[2:3], v[10:13], off offset:3072
	v_lshl_add_u32 v2, v200, 8, v20
	v_add_u32_e32 v6, 0x1e000, v0
	v_mov_b32_e32 v7, v1
	ds_read_b128 v[2:5], v2
	v_lshl_add_u64 v[6:7], s[0:1], 0, v[6:7]
	v_lshlrev_b32_e32 v8, 1, v170
	v_mov_b32_e32 v9, v1
	v_lshl_add_u64 v[10:11], v[6:7], 0, v[8:9]
	v_lshl_add_u32 v6, v202, 8, v20
	ds_read_b128 v[6:9], v6
	v_add_u32_e32 v0, 0x23000, v0
	s_waitcnt lgkmcnt(1)
	global_store_dwordx4 v[10:11], v[2:5], off offset:3072
	s_nop 1
	v_lshl_add_u64 v[2:3], s[0:1], 0, v[0:1]
	v_lshlrev_b32_e32 v0, 1, v174
	v_lshl_add_u64 v[2:3], v[2:3], 0, v[0:1]
	s_waitcnt lgkmcnt(0)
	global_store_dwordx4 v[2:3], v[6:9], off offset:3072
	s_waitcnt lgkmcnt(0)
	s_cbranch_execz .LBB0_318
	s_branch .LBB0_400
	s_nop 0
	s_nop 0
	s_nop 0
	s_nop 0
	s_nop 0
	s_nop 0
	s_nop 0
	s_nop 0
